# side-GEMM epilogue hoist, phase A gain-bias hoist and batched modulation loads, final LN hoist with counted waits, NA ctx epilogue
# speedup vs baseline: 1.0717x; 1.0125x over previous
.LBB0_131:
	s_and_b64 s[10:11], s[10:11], exec
	v_readlane_b32 s10, v252, 32
	v_ashrrev_i32_e32 v181, 31, v180
	v_readlane_b32 s11, v252, 33
	s_cselect_b32 s1, s52, s78
	s_cselect_b32 s12, s53, s79
	s_cselect_b32 s13, s56, s33
	s_cselect_b32 s16, s57, s73
	s_and_b64 s[10:11], s[10:11], exec
	v_lshlrev_b64 v[194:195], 12, v[180:181]
	s_cselect_b32 s39, s16, s12
	s_cselect_b32 s38, s13, s1
	v_lshl_or_b32 v194, v188, 2, v194
	v_lshl_add_u64 v[208:209], s[38:39], 0, v[194:195]
	global_load_dwordx4 v[222:225], v[208:209], off
	global_load_dwordx4 v[226:229], v[208:209], off offset:64
	global_load_dwordx4 v[230:233], v[208:209], off offset:512
	global_load_dwordx4 v[234:237], v[208:209], off offset:576
	v_readlane_b32 s10, v252, 35
	s_waitcnt vmcnt(3)
	v_pk_add_f32 v[132:133], v[132:133], 1.0 op_sel_hi:[1,0]
	v_pk_add_f32 v[130:131], v[130:131], 1.0 op_sel_hi:[1,0]
	v_readlane_b32 s11, v252, 36
	s_and_b64 vcc, exec, s[36:37]
	v_sub_f32_e32 v223, v223, v186
	v_sub_f32_e32 v222, v222, v186
	v_sub_f32_e32 v225, v225, v186
	v_sub_f32_e32 v224, v224, v186
	v_pk_mul_f32 v[224:225], v[184:185], v[224:225] op_sel_hi:[0,1]
	v_pk_mul_f32 v[222:223], v[184:185], v[222:223] op_sel_hi:[0,1]
	v_pk_fma_f32 v[222:223], v[152:153], v[222:223], v[156:157]
	v_pk_fma_f32 v[224:225], v[150:151], v[224:225], v[154:155]
	v_lshl_add_u64 v[194:195], s[10:11], 0, v[194:195]
	v_pk_fma_f32 v[128:129], v[128:129], v[132:133], v[224:225]
	v_pk_fma_f32 v[126:127], v[126:127], v[130:131], v[222:223]
	global_store_dwordx4 v[194:195], v[126:129], off
	s_nop 0
	s_nop 0
	v_pk_add_f32 v[126:127], v[136:137], 1.0 op_sel_hi:[1,0]
	v_pk_add_f32 v[128:129], v[134:135], 1.0 op_sel_hi:[1,0]
	s_waitcnt vmcnt(3)
	v_sub_f32_e32 v135, v227, v186
	v_sub_f32_e32 v134, v226, v186
	v_sub_f32_e32 v137, v229, v186
	v_sub_f32_e32 v136, v228, v186
	v_pk_mul_f32 v[136:137], v[184:185], v[136:137] op_sel_hi:[0,1]
	v_pk_mul_f32 v[134:135], v[184:185], v[134:135] op_sel_hi:[0,1]
	v_pk_fma_f32 v[134:135], v[146:147], v[134:135], v[148:149]
	v_pk_fma_f32 v[136:137], v[158:159], v[136:137], v[164:165]
	v_pk_fma_f32 v[122:123], v[122:123], v[128:129], v[134:135]
	v_pk_fma_f32 v[124:125], v[124:125], v[126:127], v[136:137]
	global_store_dwordx4 v[194:195], v[122:125], off offset:64
	s_nop 0
	s_waitcnt vmcnt(3)
	v_sub_f32_e32 v231, v231, v186
	v_sub_f32_e32 v230, v230, v186
	v_sub_f32_e32 v233, v233, v186
	v_sub_f32_e32 v232, v232, v186
	v_pk_mul_f32 v[232:233], v[184:185], v[232:233] op_sel_hi:[0,1]
	v_pk_mul_f32 v[230:231], v[184:185], v[230:231] op_sel_hi:[0,1]
	v_pk_add_f32 v[122:123], v[140:141], 1.0 op_sel_hi:[1,0]
	v_pk_add_f32 v[124:125], v[138:139], 1.0 op_sel_hi:[1,0]
	v_pk_fma_f32 v[230:231], v[168:169], v[230:231], v[172:173]
	v_pk_fma_f32 v[232:233], v[166:167], v[232:233], v[170:171]
	v_pk_fma_f32 v[118:119], v[118:119], v[124:125], v[230:231]
	v_pk_fma_f32 v[120:121], v[120:121], v[122:123], v[232:233]
	global_store_dwordx4 v[194:195], v[118:121], off offset:512
	s_nop 0
	s_waitcnt vmcnt(3)
	v_sub_f32_e32 v235, v235, v186
	v_sub_f32_e32 v234, v234, v186
	v_sub_f32_e32 v237, v237, v186
	v_sub_f32_e32 v236, v236, v186
	v_pk_mul_f32 v[236:237], v[184:185], v[236:237] op_sel_hi:[0,1]
	v_pk_mul_f32 v[234:235], v[184:185], v[234:235] op_sel_hi:[0,1]
	v_pk_add_f32 v[118:119], v[144:145], 1.0 op_sel_hi:[1,0]
	v_pk_add_f32 v[120:121], v[142:143], 1.0 op_sel_hi:[1,0]
	v_pk_fma_f32 v[234:235], v[160:161], v[234:235], v[162:163]
	v_pk_fma_f32 v[236:237], v[174:175], v[236:237], v[176:177]
	v_pk_fma_f32 v[114:115], v[114:115], v[120:121], v[234:235]
	v_pk_fma_f32 v[116:117], v[116:117], v[118:119], v[236:237]
	global_store_dwordx4 v[194:195], v[114:117], off offset:576
	s_cbranch_vccnz .LBB0_133
	s_nop 0
	v_or_b32_e32 v114, 16, v178
	v_ashrrev_i32_e32 v115, 31, v114
	v_lshl_add_u64 v[114:115], v[114:115], 3, s[8:9]
	global_load_dwordx2 v[182:183], v[114:115], off
	s_waitcnt vmcnt(0)
	v_mov_b32_e32 v0, v183
.LBB0_133:
	s_nop 0
	v_or_b32_e32 v114, 16, v180
	v_ashrrev_i32_e32 v115, 31, v114
	v_lshlrev_b64 v[134:135], 12, v[114:115]
	v_lshl_or_b32 v134, v188, 2, v134
	v_lshl_add_u64 v[136:137], s[38:39], 0, v[134:135]
	global_load_dwordx4 v[222:225], v[136:137], off
	global_load_dwordx4 v[226:229], v[136:137], off offset:64
	global_load_dwordx4 v[230:233], v[136:137], off offset:512
	global_load_dwordx4 v[234:237], v[136:137], off offset:576
	v_readlane_b32 s10, v252, 35
	v_readlane_b32 s11, v252, 36
	s_and_b64 vcc, exec, s[36:37]
	s_waitcnt vmcnt(3)
	v_sub_f32_e32 v223, v223, v182
	v_sub_f32_e32 v222, v222, v182
	v_sub_f32_e32 v225, v225, v182
	v_sub_f32_e32 v224, v224, v182
	v_pk_mul_f32 v[224:225], v[0:1], v[224:225] op_sel_hi:[0,1]
	v_pk_mul_f32 v[222:223], v[0:1], v[222:223] op_sel_hi:[0,1]
	v_pk_fma_f32 v[222:223], v[152:153], v[222:223], v[156:157]
	v_pk_fma_f32 v[224:225], v[150:151], v[224:225], v[154:155]
	v_lshl_add_u64 v[134:135], s[10:11], 0, v[134:135]
	v_pk_fma_f32 v[112:113], v[112:113], v[132:133], v[224:225]
	v_pk_fma_f32 v[110:111], v[110:111], v[130:131], v[222:223]
	global_store_dwordx4 v[134:135], v[110:113], off
	s_nop 0
	s_waitcnt vmcnt(3)
	v_sub_f32_e32 v227, v227, v182
	v_sub_f32_e32 v226, v226, v182
	v_sub_f32_e32 v229, v229, v182
	v_sub_f32_e32 v228, v228, v182
	v_pk_mul_f32 v[228:229], v[0:1], v[228:229] op_sel_hi:[0,1]
	v_pk_mul_f32 v[226:227], v[0:1], v[226:227] op_sel_hi:[0,1]
	v_pk_fma_f32 v[226:227], v[146:147], v[226:227], v[148:149]
	v_pk_fma_f32 v[228:229], v[158:159], v[228:229], v[164:165]
	v_pk_fma_f32 v[106:107], v[106:107], v[128:129], v[226:227]
	v_pk_fma_f32 v[108:109], v[108:109], v[126:127], v[228:229]
	global_store_dwordx4 v[134:135], v[106:109], off offset:64
	s_nop 0
	s_waitcnt vmcnt(3)
	v_sub_f32_e32 v231, v231, v182
	v_sub_f32_e32 v230, v230, v182
	v_sub_f32_e32 v233, v233, v182
	v_sub_f32_e32 v232, v232, v182
	v_pk_mul_f32 v[232:233], v[0:1], v[232:233] op_sel_hi:[0,1]
	v_pk_mul_f32 v[230:231], v[0:1], v[230:231] op_sel_hi:[0,1]
	v_pk_fma_f32 v[230:231], v[168:169], v[230:231], v[172:173]
	v_pk_fma_f32 v[232:233], v[166:167], v[232:233], v[170:171]
	v_pk_fma_f32 v[102:103], v[102:103], v[124:125], v[230:231]
	v_pk_fma_f32 v[104:105], v[104:105], v[122:123], v[232:233]
	global_store_dwordx4 v[134:135], v[102:105], off offset:512
	s_nop 0
	s_waitcnt vmcnt(3)
	v_sub_f32_e32 v237, v237, v182
	v_sub_f32_e32 v235, v235, v182
	v_sub_f32_e32 v234, v234, v182
	v_sub_f32_e32 v236, v236, v182
	v_pk_mul_f32 v[236:237], v[0:1], v[236:237] op_sel_hi:[0,1]
	v_pk_mul_f32 v[234:235], v[0:1], v[234:235] op_sel_hi:[0,1]
	v_pk_fma_f32 v[234:235], v[160:161], v[234:235], v[162:163]
	v_pk_fma_f32 v[236:237], v[174:175], v[236:237], v[176:177]
	v_pk_fma_f32 v[98:99], v[98:99], v[120:121], v[234:235]
	v_pk_fma_f32 v[100:101], v[100:101], v[118:119], v[236:237]
	global_store_dwordx4 v[134:135], v[98:101], off offset:576
	v_mov_b32_e32 v102, 1.0
	v_mov_b32_e32 v0, 1.0
	v_mov_b32_e32 v98, 0
	v_mov_b32_e32 v100, 0
	s_cbranch_vccnz .LBB0_135
	v_or_b32_e32 v100, 32, v178
	v_ashrrev_i32_e32 v101, 31, v100
	v_lshl_add_u64 v[100:101], v[100:101], 3, s[8:9]
	global_load_dwordx2 v[100:101], v[100:101], off
	s_waitcnt vmcnt(0)
	v_mov_b32_e32 v0, v101
.LBB0_135:
	v_or_b32_e32 v104, 32, v180
	v_ashrrev_i32_e32 v105, 31, v104
	v_lshlrev_b64 v[108:109], 12, v[104:105]
	v_lshl_or_b32 v108, v188, 2, v108
	v_lshl_add_u64 v[110:111], s[38:39], 0, v[108:109]
	global_load_dwordx4 v[222:225], v[110:111], off
	global_load_dwordx4 v[226:229], v[110:111], off offset:64
	global_load_dwordx4 v[230:233], v[110:111], off offset:512
	global_load_dwordx4 v[234:237], v[110:111], off offset:576
	v_readlane_b32 s10, v252, 35
	v_readlane_b32 s11, v252, 36
	s_and_b64 vcc, exec, s[36:37]
	s_waitcnt vmcnt(3)
	v_sub_f32_e32 v223, v223, v100
	v_sub_f32_e32 v222, v222, v100
	v_sub_f32_e32 v225, v225, v100
	v_sub_f32_e32 v224, v224, v100
	v_pk_mul_f32 v[224:225], v[0:1], v[224:225] op_sel_hi:[0,1]
	v_pk_mul_f32 v[222:223], v[0:1], v[222:223] op_sel_hi:[0,1]
	v_pk_fma_f32 v[222:223], v[152:153], v[222:223], v[156:157]
	v_pk_fma_f32 v[224:225], v[150:151], v[224:225], v[154:155]
	v_lshl_add_u64 v[108:109], s[10:11], 0, v[108:109]
	v_pk_fma_f32 v[96:97], v[96:97], v[132:133], v[224:225]
	v_pk_fma_f32 v[94:95], v[94:95], v[130:131], v[222:223]
	global_store_dwordx4 v[108:109], v[94:97], off
	s_nop 0
	s_waitcnt vmcnt(3)
	v_sub_f32_e32 v227, v227, v100
	v_sub_f32_e32 v226, v226, v100
	v_sub_f32_e32 v229, v229, v100
	v_sub_f32_e32 v228, v228, v100
	v_pk_mul_f32 v[228:229], v[0:1], v[228:229] op_sel_hi:[0,1]
	v_pk_mul_f32 v[226:227], v[0:1], v[226:227] op_sel_hi:[0,1]
	v_pk_fma_f32 v[226:227], v[146:147], v[226:227], v[148:149]
	v_pk_fma_f32 v[228:229], v[158:159], v[228:229], v[164:165]
	v_pk_fma_f32 v[90:91], v[90:91], v[128:129], v[226:227]
	v_pk_fma_f32 v[92:93], v[92:93], v[126:127], v[228:229]
	global_store_dwordx4 v[108:109], v[90:93], off offset:64
	s_nop 0
	s_waitcnt vmcnt(3)
	v_sub_f32_e32 v231, v231, v100
	v_sub_f32_e32 v230, v230, v100
	v_sub_f32_e32 v233, v233, v100
	v_sub_f32_e32 v232, v232, v100
	v_pk_mul_f32 v[232:233], v[0:1], v[232:233] op_sel_hi:[0,1]
	v_pk_mul_f32 v[230:231], v[0:1], v[230:231] op_sel_hi:[0,1]
	v_pk_fma_f32 v[230:231], v[168:169], v[230:231], v[172:173]
	v_pk_fma_f32 v[232:233], v[166:167], v[232:233], v[170:171]
	v_pk_fma_f32 v[86:87], v[86:87], v[124:125], v[230:231]
	v_pk_fma_f32 v[88:89], v[88:89], v[122:123], v[232:233]
	global_store_dwordx4 v[108:109], v[86:89], off offset:512
	s_nop 0
	s_waitcnt vmcnt(3)
	v_sub_f32_e32 v235, v235, v100
	v_sub_f32_e32 v234, v234, v100
	v_sub_f32_e32 v237, v237, v100
	v_sub_f32_e32 v236, v236, v100
	v_pk_mul_f32 v[236:237], v[0:1], v[236:237] op_sel_hi:[0,1]
	v_pk_mul_f32 v[234:235], v[0:1], v[234:235] op_sel_hi:[0,1]
	v_pk_fma_f32 v[234:235], v[160:161], v[234:235], v[162:163]
	v_pk_fma_f32 v[236:237], v[174:175], v[236:237], v[176:177]
	v_pk_fma_f32 v[82:83], v[82:83], v[120:121], v[234:235]
	v_pk_fma_f32 v[84:85], v[84:85], v[118:119], v[236:237]
	global_store_dwordx4 v[108:109], v[82:85], off offset:576
	s_cbranch_vccnz .LBB0_137
	s_nop 0
	v_or_b32_e32 v82, 48, v178
	v_ashrrev_i32_e32 v83, 31, v82
	v_lshl_add_u64 v[82:83], v[82:83], 3, s[8:9]
	global_load_dwordx2 v[98:99], v[82:83], off
	s_waitcnt vmcnt(0)
	v_mov_b32_e32 v102, v99
.LBB0_137:
	s_nop 0
	v_or_b32_e32 v82, 48, v180
	v_ashrrev_i32_e32 v83, 31, v82
	v_lshlrev_b64 v[86:87], 12, v[82:83]
	v_lshl_or_b32 v86, v188, 2, v86
	v_lshl_add_u64 v[88:89], s[38:39], 0, v[86:87]
	global_load_dwordx4 v[222:225], v[88:89], off
	global_load_dwordx4 v[226:229], v[88:89], off offset:64
	global_load_dwordx4 v[230:233], v[88:89], off offset:512
	global_load_dwordx4 v[234:237], v[88:89], off offset:576
	v_readlane_b32 s10, v252, 35
	v_readlane_b32 s11, v252, 36
	v_mov_b32_e32 v0, 1.0
	s_and_b64 vcc, exec, s[36:37]
	v_lshl_add_u64 v[86:87], s[10:11], 0, v[86:87]
	s_waitcnt vmcnt(3)
	v_sub_f32_e32 v223, v223, v98
	v_sub_f32_e32 v222, v222, v98
	v_sub_f32_e32 v225, v225, v98
	v_sub_f32_e32 v224, v224, v98
	v_pk_mul_f32 v[224:225], v[102:103], v[224:225] op_sel_hi:[0,1]
	v_pk_mul_f32 v[222:223], v[102:103], v[222:223] op_sel_hi:[0,1]
	v_pk_fma_f32 v[222:223], v[152:153], v[222:223], v[156:157]
	v_pk_fma_f32 v[224:225], v[150:151], v[224:225], v[154:155]
	v_pk_fma_f32 v[78:79], v[78:79], v[130:131], v[222:223]
	v_pk_fma_f32 v[80:81], v[80:81], v[132:133], v[224:225]
	global_store_dwordx4 v[86:87], v[78:81], off
	s_nop 0
	s_waitcnt vmcnt(3)
	v_sub_f32_e32 v227, v227, v98
	v_sub_f32_e32 v226, v226, v98
	v_sub_f32_e32 v229, v229, v98
	v_sub_f32_e32 v228, v228, v98
	v_pk_mul_f32 v[228:229], v[102:103], v[228:229] op_sel_hi:[0,1]
	v_pk_mul_f32 v[226:227], v[102:103], v[226:227] op_sel_hi:[0,1]
	v_pk_fma_f32 v[226:227], v[146:147], v[226:227], v[148:149]
	v_pk_fma_f32 v[228:229], v[158:159], v[228:229], v[164:165]
	v_pk_fma_f32 v[74:75], v[74:75], v[128:129], v[226:227]
	v_pk_fma_f32 v[76:77], v[76:77], v[126:127], v[228:229]
	global_store_dwordx4 v[86:87], v[74:77], off offset:64
	s_nop 0
	s_waitcnt vmcnt(3)
	v_sub_f32_e32 v231, v231, v98
	v_sub_f32_e32 v230, v230, v98
	v_sub_f32_e32 v233, v233, v98
	v_sub_f32_e32 v232, v232, v98
	v_pk_mul_f32 v[232:233], v[102:103], v[232:233] op_sel_hi:[0,1]
	v_pk_mul_f32 v[230:231], v[102:103], v[230:231] op_sel_hi:[0,1]
	v_pk_fma_f32 v[230:231], v[168:169], v[230:231], v[172:173]
	v_pk_fma_f32 v[232:233], v[166:167], v[232:233], v[170:171]
	v_pk_fma_f32 v[70:71], v[70:71], v[124:125], v[230:231]
	v_pk_fma_f32 v[72:73], v[72:73], v[122:123], v[232:233]
	global_store_dwordx4 v[86:87], v[70:73], off offset:512
	s_nop 0
	s_waitcnt vmcnt(3)
	v_sub_f32_e32 v235, v235, v98
	v_sub_f32_e32 v234, v234, v98
	v_sub_f32_e32 v237, v237, v98
	v_sub_f32_e32 v236, v236, v98
	v_pk_mul_f32 v[236:237], v[102:103], v[236:237] op_sel_hi:[0,1]
	v_pk_mul_f32 v[234:235], v[102:103], v[234:235] op_sel_hi:[0,1]
	v_pk_fma_f32 v[234:235], v[160:161], v[234:235], v[162:163]
	v_pk_fma_f32 v[236:237], v[174:175], v[236:237], v[176:177]
	v_pk_fma_f32 v[66:67], v[66:67], v[120:121], v[234:235]
	v_pk_fma_f32 v[68:69], v[68:69], v[118:119], v[236:237]
	global_store_dwordx4 v[86:87], v[66:69], off offset:576
	v_mov_b32_e32 v72, 0
	v_mov_b32_e32 v70, 1.0
	v_mov_b32_e32 v66, 0
	s_cbranch_vccnz .LBB0_139
	v_lshl_add_u64 v[68:69], v[178:179], 3, s[8:9]
	global_load_dwordx2 v[72:73], v[68:69], off offset:1024
	s_waitcnt vmcnt(0)
	v_mov_b32_e32 v70, v73
.LBB0_139:
	v_lshlrev_b64 v[68:69], 12, v[180:181]
	v_lshl_or_b32 v68, v188, 2, v68
	s_mov_b64 s[10:11], 0x80000
	v_lshl_add_u64 v[78:79], v[68:69], 0, s[10:11]
	v_lshl_add_u64 v[80:81], s[38:39], 0, v[78:79]
	global_load_dwordx4 v[222:225], v[80:81], off
	global_load_dwordx4 v[226:229], v[80:81], off offset:64
	global_load_dwordx4 v[230:233], v[80:81], off offset:512
	global_load_dwordx4 v[234:237], v[80:81], off offset:576
	v_readlane_b32 s10, v252, 35
	v_readlane_b32 s11, v252, 36
	s_and_b64 vcc, exec, s[36:37]
	s_waitcnt vmcnt(3)
	v_sub_f32_e32 v223, v223, v72
	v_sub_f32_e32 v222, v222, v72
	v_sub_f32_e32 v225, v225, v72
	v_sub_f32_e32 v224, v224, v72
	v_pk_mul_f32 v[224:225], v[70:71], v[224:225] op_sel_hi:[0,1]
	v_pk_mul_f32 v[222:223], v[70:71], v[222:223] op_sel_hi:[0,1]
	v_pk_fma_f32 v[222:223], v[152:153], v[222:223], v[156:157]
	v_pk_fma_f32 v[224:225], v[150:151], v[224:225], v[154:155]
	v_lshl_add_u64 v[78:79], s[10:11], 0, v[78:79]
	v_pk_fma_f32 v[64:65], v[64:65], v[132:133], v[224:225]
	v_pk_fma_f32 v[62:63], v[62:63], v[130:131], v[222:223]
	global_store_dwordx4 v[78:79], v[62:65], off
	s_nop 0
	s_waitcnt vmcnt(3)
	v_sub_f32_e32 v227, v227, v72
	v_sub_f32_e32 v226, v226, v72
	v_sub_f32_e32 v229, v229, v72
	v_sub_f32_e32 v228, v228, v72
	v_pk_mul_f32 v[228:229], v[70:71], v[228:229] op_sel_hi:[0,1]
	v_pk_mul_f32 v[226:227], v[70:71], v[226:227] op_sel_hi:[0,1]
	v_pk_fma_f32 v[226:227], v[146:147], v[226:227], v[148:149]
	v_pk_fma_f32 v[228:229], v[158:159], v[228:229], v[164:165]
	v_pk_fma_f32 v[58:59], v[58:59], v[128:129], v[226:227]
	v_pk_fma_f32 v[60:61], v[60:61], v[126:127], v[228:229]
	global_store_dwordx4 v[78:79], v[58:61], off offset:64
	s_nop 0
	s_waitcnt vmcnt(3)
	v_sub_f32_e32 v231, v231, v72
	v_sub_f32_e32 v230, v230, v72
	v_sub_f32_e32 v233, v233, v72
	v_sub_f32_e32 v232, v232, v72
	v_pk_mul_f32 v[232:233], v[70:71], v[232:233] op_sel_hi:[0,1]
	v_pk_mul_f32 v[230:231], v[70:71], v[230:231] op_sel_hi:[0,1]
	v_pk_fma_f32 v[230:231], v[168:169], v[230:231], v[172:173]
	v_pk_fma_f32 v[232:233], v[166:167], v[232:233], v[170:171]
	v_pk_fma_f32 v[54:55], v[54:55], v[124:125], v[230:231]
	v_pk_fma_f32 v[56:57], v[56:57], v[122:123], v[232:233]
	global_store_dwordx4 v[78:79], v[54:57], off offset:512
	s_nop 0
	s_waitcnt vmcnt(3)
	v_sub_f32_e32 v235, v235, v72
	v_sub_f32_e32 v234, v234, v72
	v_sub_f32_e32 v237, v237, v72
	v_sub_f32_e32 v236, v236, v72
	v_pk_mul_f32 v[236:237], v[70:71], v[236:237] op_sel_hi:[0,1]
	v_pk_mul_f32 v[234:235], v[70:71], v[234:235] op_sel_hi:[0,1]
	v_pk_fma_f32 v[234:235], v[160:161], v[234:235], v[162:163]
	v_pk_fma_f32 v[236:237], v[174:175], v[236:237], v[176:177]
	v_pk_fma_f32 v[50:51], v[50:51], v[120:121], v[234:235]
	v_pk_fma_f32 v[52:53], v[52:53], v[118:119], v[236:237]
	global_store_dwordx4 v[78:79], v[50:53], off offset:576
	s_cbranch_vccnz .LBB0_141
	s_nop 0
	v_lshl_add_u64 v[50:51], v[178:179], 3, s[8:9]
	global_load_dwordx2 v[66:67], v[50:51], off offset:1152
	s_waitcnt vmcnt(0)
	v_mov_b32_e32 v0, v67
.LBB0_141:
	s_mov_b64 s[10:11], 0x90000
	v_lshl_add_u64 v[54:55], v[68:69], 0, s[10:11]
	v_lshl_add_u64 v[56:57], s[38:39], 0, v[54:55]
	global_load_dwordx4 v[222:225], v[56:57], off
	global_load_dwordx4 v[226:229], v[56:57], off offset:64
	global_load_dwordx4 v[230:233], v[56:57], off offset:512
	global_load_dwordx4 v[234:237], v[56:57], off offset:576
	v_readlane_b32 s10, v252, 35
	v_readlane_b32 s11, v252, 36
	s_and_b64 vcc, exec, s[36:37]
	s_waitcnt vmcnt(3)
	v_sub_f32_e32 v223, v223, v66
	v_sub_f32_e32 v222, v222, v66
	v_sub_f32_e32 v225, v225, v66
	v_sub_f32_e32 v224, v224, v66
	v_pk_mul_f32 v[224:225], v[0:1], v[224:225] op_sel_hi:[0,1]
	v_pk_mul_f32 v[222:223], v[0:1], v[222:223] op_sel_hi:[0,1]
	v_pk_fma_f32 v[222:223], v[152:153], v[222:223], v[156:157]
	v_pk_fma_f32 v[224:225], v[150:151], v[224:225], v[154:155]
	v_lshl_add_u64 v[54:55], s[10:11], 0, v[54:55]
	v_pk_fma_f32 v[48:49], v[48:49], v[132:133], v[224:225]
	v_pk_fma_f32 v[46:47], v[46:47], v[130:131], v[222:223]
	global_store_dwordx4 v[54:55], v[46:49], off
	s_nop 0
	s_waitcnt vmcnt(3)
	v_sub_f32_e32 v227, v227, v66
	v_sub_f32_e32 v226, v226, v66
	v_sub_f32_e32 v229, v229, v66
	v_sub_f32_e32 v228, v228, v66
	v_pk_mul_f32 v[228:229], v[0:1], v[228:229] op_sel_hi:[0,1]
	v_pk_mul_f32 v[226:227], v[0:1], v[226:227] op_sel_hi:[0,1]
	v_pk_fma_f32 v[226:227], v[146:147], v[226:227], v[148:149]
	v_pk_fma_f32 v[228:229], v[158:159], v[228:229], v[164:165]
	v_pk_fma_f32 v[42:43], v[42:43], v[128:129], v[226:227]
	v_pk_fma_f32 v[44:45], v[44:45], v[126:127], v[228:229]
	global_store_dwordx4 v[54:55], v[42:45], off offset:64
	s_nop 0
	s_waitcnt vmcnt(3)
	v_sub_f32_e32 v231, v231, v66
	v_sub_f32_e32 v230, v230, v66
	v_sub_f32_e32 v233, v233, v66
	v_sub_f32_e32 v232, v232, v66
	v_pk_mul_f32 v[232:233], v[0:1], v[232:233] op_sel_hi:[0,1]
	v_pk_mul_f32 v[230:231], v[0:1], v[230:231] op_sel_hi:[0,1]
	v_pk_fma_f32 v[230:231], v[168:169], v[230:231], v[172:173]
	v_pk_fma_f32 v[232:233], v[166:167], v[232:233], v[170:171]
	v_pk_fma_f32 v[38:39], v[38:39], v[124:125], v[230:231]
	v_pk_fma_f32 v[40:41], v[40:41], v[122:123], v[232:233]
	global_store_dwordx4 v[54:55], v[38:41], off offset:512
	s_nop 0
	s_waitcnt vmcnt(3)
	v_sub_f32_e32 v237, v237, v66
	v_sub_f32_e32 v235, v235, v66
	v_sub_f32_e32 v234, v234, v66
	v_sub_f32_e32 v236, v236, v66
	v_pk_mul_f32 v[236:237], v[0:1], v[236:237] op_sel_hi:[0,1]
	v_pk_mul_f32 v[234:235], v[0:1], v[234:235] op_sel_hi:[0,1]
	v_pk_fma_f32 v[234:235], v[160:161], v[234:235], v[162:163]
	v_pk_fma_f32 v[236:237], v[174:175], v[236:237], v[176:177]
	v_pk_fma_f32 v[34:35], v[34:35], v[120:121], v[234:235]
	v_pk_fma_f32 v[36:37], v[36:37], v[118:119], v[236:237]
	global_store_dwordx4 v[54:55], v[34:37], off offset:576
	v_mov_b32_e32 v38, 1.0
	v_mov_b32_e32 v40, 0
	v_mov_b32_e32 v34, 0
	v_mov_b32_e32 v0, 1.0
	s_cbranch_vccnz .LBB0_143
	v_lshl_add_u64 v[36:37], v[178:179], 3, s[8:9]
	global_load_dwordx2 v[40:41], v[36:37], off offset:1280
	s_waitcnt vmcnt(0)
	v_mov_b32_e32 v0, v41
.LBB0_143:
	v_lshlrev_b64 v[36:37], 12, v[180:181]
	v_lshl_or_b32 v36, v188, 2, v36
	s_mov_b64 s[10:11], 0xa0000
	v_lshl_add_u64 v[46:47], v[36:37], 0, s[10:11]
	v_lshl_add_u64 v[48:49], s[38:39], 0, v[46:47]
	global_load_dwordx4 v[222:225], v[48:49], off
	global_load_dwordx4 v[226:229], v[48:49], off offset:64
	global_load_dwordx4 v[230:233], v[48:49], off offset:512
	global_load_dwordx4 v[234:237], v[48:49], off offset:576
	v_readlane_b32 s10, v252, 35
	v_readlane_b32 s11, v252, 36
	s_and_b64 vcc, exec, s[36:37]
	s_waitcnt vmcnt(3)
	v_sub_f32_e32 v223, v223, v40
	v_sub_f32_e32 v222, v222, v40
	v_sub_f32_e32 v225, v225, v40
	v_sub_f32_e32 v224, v224, v40
	v_pk_mul_f32 v[224:225], v[0:1], v[224:225] op_sel_hi:[0,1]
	v_pk_mul_f32 v[222:223], v[0:1], v[222:223] op_sel_hi:[0,1]
	v_pk_fma_f32 v[222:223], v[152:153], v[222:223], v[156:157]
	v_pk_fma_f32 v[224:225], v[150:151], v[224:225], v[154:155]
	v_lshl_add_u64 v[46:47], s[10:11], 0, v[46:47]
	v_pk_fma_f32 v[32:33], v[32:33], v[132:133], v[224:225]
	v_pk_fma_f32 v[30:31], v[30:31], v[130:131], v[222:223]
	global_store_dwordx4 v[46:47], v[30:33], off
	s_nop 0
	s_waitcnt vmcnt(3)
	v_sub_f32_e32 v227, v227, v40
	v_sub_f32_e32 v226, v226, v40
	v_sub_f32_e32 v229, v229, v40
	v_sub_f32_e32 v228, v228, v40
	v_pk_mul_f32 v[228:229], v[0:1], v[228:229] op_sel_hi:[0,1]
	v_pk_mul_f32 v[226:227], v[0:1], v[226:227] op_sel_hi:[0,1]
	v_pk_fma_f32 v[226:227], v[146:147], v[226:227], v[148:149]
	v_pk_fma_f32 v[228:229], v[158:159], v[228:229], v[164:165]
	v_pk_fma_f32 v[26:27], v[26:27], v[128:129], v[226:227]
	v_pk_fma_f32 v[28:29], v[28:29], v[126:127], v[228:229]
	global_store_dwordx4 v[46:47], v[26:29], off offset:64
	s_nop 0
	s_waitcnt vmcnt(3)
	v_sub_f32_e32 v231, v231, v40
	v_sub_f32_e32 v230, v230, v40
	v_sub_f32_e32 v233, v233, v40
	v_sub_f32_e32 v232, v232, v40
	v_pk_mul_f32 v[232:233], v[0:1], v[232:233] op_sel_hi:[0,1]
	v_pk_mul_f32 v[230:231], v[0:1], v[230:231] op_sel_hi:[0,1]
	v_pk_fma_f32 v[230:231], v[168:169], v[230:231], v[172:173]
	v_pk_fma_f32 v[232:233], v[166:167], v[232:233], v[170:171]
	v_pk_fma_f32 v[22:23], v[22:23], v[124:125], v[230:231]
	v_pk_fma_f32 v[24:25], v[24:25], v[122:123], v[232:233]
	global_store_dwordx4 v[46:47], v[22:25], off offset:512
	s_nop 0
	s_waitcnt vmcnt(3)
	v_sub_f32_e32 v235, v235, v40
	v_sub_f32_e32 v234, v234, v40
	v_sub_f32_e32 v237, v237, v40
	v_sub_f32_e32 v236, v236, v40
	v_pk_mul_f32 v[236:237], v[0:1], v[236:237] op_sel_hi:[0,1]
	v_pk_mul_f32 v[234:235], v[0:1], v[234:235] op_sel_hi:[0,1]
	v_pk_fma_f32 v[234:235], v[160:161], v[234:235], v[162:163]
	v_pk_fma_f32 v[236:237], v[174:175], v[236:237], v[176:177]
	v_pk_fma_f32 v[18:19], v[18:19], v[120:121], v[234:235]
	v_pk_fma_f32 v[20:21], v[20:21], v[118:119], v[236:237]
	global_store_dwordx4 v[46:47], v[18:21], off offset:576
	s_cbranch_vccnz .LBB0_145
	s_nop 0
	v_lshl_add_u64 v[18:19], v[178:179], 3, s[8:9]
	global_load_dwordx2 v[34:35], v[18:19], off offset:1408
	s_waitcnt vmcnt(0)
	v_mov_b32_e32 v38, v35
.LBB0_145:
	s_mov_b64 s[8:9], 0xb0000
	v_lshl_add_u64 v[22:23], v[36:37], 0, s[8:9]
	v_lshl_add_u64 v[24:25], s[38:39], 0, v[22:23]
	global_load_dwordx4 v[222:225], v[24:25], off
	global_load_dwordx4 v[226:229], v[24:25], off offset:64
	global_load_dwordx4 v[230:233], v[24:25], off offset:512
	global_load_dwordx4 v[234:237], v[24:25], off offset:576
	v_readlane_b32 s8, v252, 35
	v_readlane_b32 s9, v252, 36
	v_cmp_eq_u32_e32 vcc, 0, v185
	s_waitcnt vmcnt(3)
	v_sub_f32_e32 v223, v223, v34
	v_sub_f32_e32 v222, v222, v34
	v_sub_f32_e32 v225, v225, v34
	v_sub_f32_e32 v224, v224, v34
	v_pk_mul_f32 v[224:225], v[38:39], v[224:225] op_sel_hi:[0,1]
	v_pk_mul_f32 v[222:223], v[38:39], v[222:223] op_sel_hi:[0,1]
	v_pk_fma_f32 v[222:223], v[152:153], v[222:223], v[156:157]
	v_pk_fma_f32 v[224:225], v[150:151], v[224:225], v[154:155]
	v_lshl_add_u64 v[22:23], s[8:9], 0, v[22:23]
	v_pk_fma_f32 v[16:17], v[16:17], v[132:133], v[224:225]
	v_pk_fma_f32 v[14:15], v[14:15], v[130:131], v[222:223]
	global_store_dwordx4 v[22:23], v[14:17], off
	s_nop 0
	s_waitcnt vmcnt(3)
	v_sub_f32_e32 v227, v227, v34
	v_sub_f32_e32 v226, v226, v34
	v_sub_f32_e32 v229, v229, v34
	v_sub_f32_e32 v228, v228, v34
	v_pk_mul_f32 v[228:229], v[38:39], v[228:229] op_sel_hi:[0,1]
	v_pk_mul_f32 v[226:227], v[38:39], v[226:227] op_sel_hi:[0,1]
	v_pk_fma_f32 v[226:227], v[146:147], v[226:227], v[148:149]
	v_pk_fma_f32 v[228:229], v[158:159], v[228:229], v[164:165]
	v_pk_fma_f32 v[10:11], v[10:11], v[128:129], v[226:227]
	v_pk_fma_f32 v[12:13], v[12:13], v[126:127], v[228:229]
	global_store_dwordx4 v[22:23], v[10:13], off offset:64
	s_nop 0
	s_waitcnt vmcnt(3)
	v_sub_f32_e32 v231, v231, v34
	v_sub_f32_e32 v230, v230, v34
	v_sub_f32_e32 v233, v233, v34
	v_sub_f32_e32 v232, v232, v34
	v_pk_mul_f32 v[232:233], v[38:39], v[232:233] op_sel_hi:[0,1]
	v_pk_mul_f32 v[230:231], v[38:39], v[230:231] op_sel_hi:[0,1]
	v_pk_fma_f32 v[230:231], v[168:169], v[230:231], v[172:173]
	v_pk_fma_f32 v[232:233], v[166:167], v[232:233], v[170:171]
	v_pk_fma_f32 v[6:7], v[6:7], v[124:125], v[230:231]
	v_pk_fma_f32 v[8:9], v[8:9], v[122:123], v[232:233]
	global_store_dwordx4 v[22:23], v[6:9], off offset:512
	s_nop 0
	s_waitcnt vmcnt(3)
	v_sub_f32_e32 v235, v235, v34
	v_sub_f32_e32 v234, v234, v34
	v_sub_f32_e32 v237, v237, v34
	v_sub_f32_e32 v236, v236, v34
	v_pk_mul_f32 v[236:237], v[38:39], v[236:237] op_sel_hi:[0,1]
	v_pk_mul_f32 v[234:235], v[38:39], v[234:235] op_sel_hi:[0,1]
	v_pk_fma_f32 v[234:235], v[160:161], v[234:235], v[162:163]
	v_pk_fma_f32 v[236:237], v[174:175], v[236:237], v[176:177]
	v_pk_fma_f32 v[2:3], v[2:3], v[120:121], v[234:235]
	v_pk_fma_f32 v[4:5], v[4:5], v[118:119], v[236:237]
	global_store_dwordx4 v[22:23], v[2:5], off offset:576
	s_waitcnt vmcnt(0)
	s_barrier
	s_waitcnt vmcnt(0)
	s_barrier
	s_and_saveexec_b64 s[8:9], vcc
	v_readlane_b32 s16, v252, 41
	v_readlane_b32 s36, v254, 52
	v_readlane_b32 s17, v252, 42
	v_readlane_b32 s37, v254, 53
	s_cbranch_execz .LBB0_157
	s_mov_b64 s[10:11], exec
	buffer_wbl2 sc1
	s_waitcnt vmcnt(0)
	s_waitcnt vmcnt(0)
	v_mbcnt_lo_u32_b32 v0, s10, 0
	v_mbcnt_hi_u32_b32 v0, s11, v0
	v_cmp_eq_u32_e32 vcc, 0, v0
	s_and_saveexec_b64 s[12:13], vcc
	s_cbranch_execz .LBB0_148
	s_bcnt1_i32_b64 s1, s[10:11]
	v_mov_b32_e32 v0, s1
	global_atomic_add v1, v0, s[16:17]

.LBB0_158:
	s_xor_b64 s[40:41], s[6:7], -1
	s_cmp_ge_i32 s46, s13
	s_cbranch_scc1 .LBB0_182
	s_mul_i32 s70, s86, 0x6c00
	s_lshl_b64 s[8:9], s[70:71], 2
	v_readlane_b32 s10, v252, 10
	v_readlane_b32 s11, v252, 11
	s_add_u32 s19, s10, s8
	s_mov_b32 s25, s85
	s_mov_b32 s2, s84
	s_addc_u32 s28, s11, s9
	s_add_i32 s70, s0, 0xfffffc00
	s_mov_b64 s[8:9], s[90:91]
	v_readlane_b32 s84, v252, 0
	s_lshl_b64 s[0:1], s[70:71], 2
	v_readlane_b32 s90, v252, 6
	v_readlane_b32 s91, v252, 7
	v_readlane_b32 s85, v252, 1
	s_mov_b64 s[90:91], s[8:9]
	s_add_u32 s8, s84, s0
	v_readlane_b32 s86, v252, 2
	s_addc_u32 s9, s85, s1
	v_readlane_b32 s87, v252, 3
	s_add_u32 s0, s86, s0
	v_and_b32_e32 v66, 63, v185
	s_addc_u32 s1, s87, s1
	v_lshlrev_b32_e32 v0, 4, v66
	v_lshl_add_u64 v[70:71], s[0:1], 0, v[0:1]
	v_readlane_b32 s0, v254, 17
	v_lshl_add_u64 v[68:69], s[8:9], 0, v[0:1]
	v_lshlrev_b32_e32 v0, 3, v66
	v_readlane_b32 s1, v254, 18
	s_ashr_i32 s47, s46, 31
	s_lshl_b64 s[8:9], s[46:47], 11
	v_lshl_add_u64 v[72:73], s[0:1], 0, v[0:1]
	s_lshl_b32 s0, s12, 2
	s_ashr_i32 s1, s0, 31
	v_or_b32_e32 v74, s8, v0
	v_mov_b32_e32 v75, s9
	s_lshl_b64 s[42:43], s[0:1], 11
	s_lshl_b64 s[8:9], s[46:47], 3
	s_add_u32 s29, s8, 0x1a0000
	s_addc_u32 s30, s9, 0
	s_lshl_b64 s[44:45], s[0:1], 3
	s_add_i32 s0, s46, s12
	s_ashr_i32 s1, s0, 31
	s_lshl_b32 s31, s12, 1
	s_lshl_b64 s[8:9], s[0:1], 11
	s_lshl_b64 s[0:1], s[0:1], 3
	s_add_u32 s34, s0, 0x1a0000
	v_cmp_eq_u32_e64 s[36:37], 0, v66
	v_or_b32_e32 v76, s8, v0
	v_mov_b32_e32 v77, s9
	s_addc_u32 s35, s1, 0
	s_mov_b32 s61, 0xf800000
	s_movk_i32 s68, 0x1000
	s_mov_b32 s70, 0x3200000
	s_mov_b64 s[84:85], 0x1000
	v_readlane_b32 s88, v252, 4
	v_readlane_b32 s89, v252, 5
	s_and_b64 vcc, exec, s[40:41]
	s_cbranch_vccz .Lpa_nog
	global_load_dwordx4 v[152:155], v[68:69], off
	global_load_dwordx4 v[168:171], v[70:71], off
	global_load_dwordx4 v[156:159], v[68:69], off offset:1024
	global_load_dwordx4 v[172:175], v[70:71], off offset:1024
	global_load_dwordx4 v[160:163], v[68:69], off offset:2048
	global_load_dwordx4 v[176:179], v[70:71], off offset:2048
	global_load_dwordx4 v[164:167], v[68:69], off offset:3072
	global_load_dwordx4 v[180:183], v[70:71], off offset:3072
.Lpa_nog:
	s_branch .LBB0_163
.LBB0_160:
	s_or_b64 exec, exec, s[0:1]
	v_pk_mul_f32 v[16:17], v[18:19], v[16:17] op_sel_hi:[0,1]
	v_pk_mul_f32 v[14:15], v[18:19], v[14:15] op_sel_hi:[0,1]
	v_pk_mul_f32 v[12:13], v[18:19], v[12:13] op_sel_hi:[0,1]
	v_pk_mul_f32 v[10:11], v[18:19], v[10:11] op_sel_hi:[0,1]
	v_pk_mul_f32 v[4:5], v[18:19], v[4:5] op_sel_hi:[0,1]
	v_pk_mul_f32 v[2:3], v[18:19], v[2:3] op_sel_hi:[0,1]
	v_pk_mul_f32 v[8:9], v[18:19], v[8:9] op_sel_hi:[0,1]
	v_pk_mul_f32 v[6:7], v[18:19], v[6:7] op_sel_hi:[0,1]
	v_pk_fma_f32 v[16:17], v[154:155], v[16:17], v[170:171]
	v_pk_fma_f32 v[14:15], v[152:153], v[14:15], v[168:169]
	v_pk_fma_f32 v[12:13], v[158:159], v[12:13], v[174:175]
	v_pk_fma_f32 v[10:11], v[156:157], v[10:11], v[172:173]
	v_pk_fma_f32 v[4:5], v[162:163], v[4:5], v[178:179]
	v_pk_fma_f32 v[2:3], v[160:161], v[2:3], v[176:177]
	v_pk_fma_f32 v[8:9], v[166:167], v[8:9], v[182:183]
	v_pk_fma_f32 v[6:7], v[164:165], v[6:7], v[180:181]
.LBB0_161:
	s_min_i32 s0, s8, 0x8000
	s_ashr_i32 s0, s0, 12
	s_mulk_i32 s0, 0xc00
	s_ashr_i32 s1, s0, 31
	s_lshl_b64 s[0:1], s[0:1], 2
	s_add_u32 s0, s19, s0
	s_addc_u32 s1, s28, s1
	s_add_u32 s16, s0, 0x1000
	s_addc_u32 s17, s1, 0
	global_load_dwordx4 v[120:123], v0, s[0:1]
	global_load_dwordx4 v[124:127], v0, s[0:1] offset:1024
	global_load_dwordx4 v[128:131], v0, s[0:1] offset:2048
	global_load_dwordx4 v[132:135], v0, s[0:1] offset:3072
	global_load_dwordx4 v[136:139], v0, s[16:17]
	global_load_dwordx4 v[140:143], v0, s[16:17] offset:1024
	global_load_dwordx4 v[144:147], v0, s[16:17] offset:2048
	global_load_dwordx4 v[148:151], v0, s[16:17] offset:3072
	s_ashr_i32 s9, s8, 31
	s_lshl_b64 s[8:9], s[8:9], 11
	v_lshl_add_u64 v[26:27], v[72:73], 0, s[8:9]
	s_waitcnt vmcnt(0)
	v_pk_add_f32 v[138:139], v[138:139], 1.0 op_sel_hi:[1,0]
	v_pk_add_f32 v[136:137], v[136:137], 1.0 op_sel_hi:[1,0]
	v_pk_fma_f32 v[16:17], v[16:17], v[138:139], v[122:123]
	v_pk_fma_f32 v[14:15], v[14:15], v[136:137], v[120:121]
	s_nop 0
	v_cvt_pk_bf16_f32 v14, v14, v15
	v_cvt_pk_bf16_f32 v15, v16, v17
	global_store_dwordx2 v[26:27], v[14:15], off
	v_pk_add_f32 v[142:143], v[142:143], 1.0 op_sel_hi:[1,0]
	v_pk_add_f32 v[140:141], v[140:141], 1.0 op_sel_hi:[1,0]
	v_pk_fma_f32 v[12:13], v[12:13], v[142:143], v[126:127]
	v_pk_fma_f32 v[10:11], v[10:11], v[140:141], v[124:125]
	s_nop 0
	v_cvt_pk_bf16_f32 v10, v10, v11
	v_cvt_pk_bf16_f32 v11, v12, v13
	global_store_dwordx2 v[26:27], v[10:11], off offset:512
	v_pk_add_f32 v[146:147], v[146:147], 1.0 op_sel_hi:[1,0]
	v_pk_add_f32 v[144:145], v[144:145], 1.0 op_sel_hi:[1,0]
	v_pk_fma_f32 v[4:5], v[4:5], v[146:147], v[130:131]
	v_pk_fma_f32 v[2:3], v[2:3], v[144:145], v[128:129]
	s_nop 0
	v_cvt_pk_bf16_f32 v2, v2, v3
	v_cvt_pk_bf16_f32 v3, v4, v5
	global_store_dwordx2 v[26:27], v[2:3], off offset:1024
	v_pk_add_f32 v[150:151], v[150:151], 1.0 op_sel_hi:[1,0]
	v_pk_add_f32 v[148:149], v[148:149], 1.0 op_sel_hi:[1,0]
	v_pk_fma_f32 v[8:9], v[8:9], v[150:151], v[134:135]
	v_pk_fma_f32 v[6:7], v[6:7], v[148:149], v[132:133]
	s_nop 0
	v_cvt_pk_bf16_f32 v6, v6, v7
	v_cvt_pk_bf16_f32 v7, v8, v9
	global_store_dwordx2 v[26:27], v[6:7], off offset:1536

.LBB0_166:
	s_or_b64 exec, exec, s[0:1]
	v_pk_mul_f32 v[64:65], v[78:79], v[64:65] op_sel_hi:[0,1]
	v_pk_mul_f32 v[62:63], v[78:79], v[62:63] op_sel_hi:[0,1]
	v_pk_mul_f32 v[60:61], v[78:79], v[60:61] op_sel_hi:[0,1]
	v_pk_mul_f32 v[58:59], v[78:79], v[58:59] op_sel_hi:[0,1]
	v_pk_mul_f32 v[56:57], v[78:79], v[56:57] op_sel_hi:[0,1]
	v_pk_mul_f32 v[54:55], v[78:79], v[54:55] op_sel_hi:[0,1]
	v_pk_mul_f32 v[52:53], v[78:79], v[52:53] op_sel_hi:[0,1]
	v_pk_mul_f32 v[50:51], v[78:79], v[50:51] op_sel_hi:[0,1]
	v_pk_fma_f32 v[64:65], v[154:155], v[64:65], v[170:171]
	v_pk_fma_f32 v[62:63], v[152:153], v[62:63], v[168:169]
	v_pk_fma_f32 v[60:61], v[158:159], v[60:61], v[174:175]
	v_pk_fma_f32 v[58:59], v[156:157], v[58:59], v[172:173]
	v_pk_fma_f32 v[56:57], v[162:163], v[56:57], v[178:179]
	v_pk_fma_f32 v[54:55], v[160:161], v[54:55], v[176:177]
	v_pk_fma_f32 v[52:53], v[166:167], v[52:53], v[182:183]
	v_pk_fma_f32 v[50:51], v[164:165], v[50:51], v[180:181]
.LBB0_167:
	s_min_i32 s0, s46, 0x8000
	s_ashr_i32 s0, s0, 12
	s_mulk_i32 s0, 0xc00
	s_ashr_i32 s1, s0, 31
	s_lshl_b64 s[0:1], s[0:1], 2
	s_add_u32 s0, s19, s0
	s_addc_u32 s1, s28, s1
	s_add_u32 s16, s0, 0x1000
	s_addc_u32 s17, s1, 0
	global_load_dwordx4 v[120:123], v0, s[0:1]
	global_load_dwordx4 v[124:127], v0, s[0:1] offset:1024
	global_load_dwordx4 v[128:131], v0, s[0:1] offset:2048
	global_load_dwordx4 v[132:135], v0, s[0:1] offset:3072
	global_load_dwordx4 v[136:139], v0, s[16:17]
	global_load_dwordx4 v[140:143], v0, s[16:17] offset:1024
	global_load_dwordx4 v[144:147], v0, s[16:17] offset:2048
	global_load_dwordx4 v[148:151], v0, s[16:17] offset:3072
	v_lshl_add_u64 v[88:89], s[90:91], 0, v[74:75]
	v_add_co_u32_e32 v88, vcc, s70, v88
	v_addc_co_u32_e32 v89, vcc, 0, v89, vcc
	s_waitcnt vmcnt(0)
	v_pk_add_f32 v[138:139], v[138:139], 1.0 op_sel_hi:[1,0]
	v_pk_add_f32 v[136:137], v[136:137], 1.0 op_sel_hi:[1,0]
	v_pk_fma_f32 v[64:65], v[64:65], v[138:139], v[122:123]
	v_pk_fma_f32 v[62:63], v[62:63], v[136:137], v[120:121]
	s_nop 0
	v_cvt_pk_bf16_f32 v62, v62, v63
	v_cvt_pk_bf16_f32 v63, v64, v65
	global_store_dwordx2 v[88:89], v[62:63], off
	v_pk_add_f32 v[142:143], v[142:143], 1.0 op_sel_hi:[1,0]
	v_pk_add_f32 v[140:141], v[140:141], 1.0 op_sel_hi:[1,0]
	v_pk_fma_f32 v[60:61], v[60:61], v[142:143], v[126:127]
	v_pk_fma_f32 v[58:59], v[58:59], v[140:141], v[124:125]
	s_nop 0
	v_cvt_pk_bf16_f32 v58, v58, v59
	v_cvt_pk_bf16_f32 v59, v60, v61
	global_store_dwordx2 v[88:89], v[58:59], off offset:512
	v_pk_add_f32 v[146:147], v[146:147], 1.0 op_sel_hi:[1,0]
	v_pk_add_f32 v[144:145], v[144:145], 1.0 op_sel_hi:[1,0]
	v_pk_fma_f32 v[56:57], v[56:57], v[146:147], v[130:131]
	v_pk_fma_f32 v[54:55], v[54:55], v[144:145], v[128:129]
	s_nop 0
	v_cvt_pk_bf16_f32 v54, v54, v55
	v_cvt_pk_bf16_f32 v55, v56, v57
	global_store_dwordx2 v[88:89], v[54:55], off offset:1024
	v_pk_add_f32 v[150:151], v[150:151], 1.0 op_sel_hi:[1,0]
	v_pk_add_f32 v[148:149], v[148:149], 1.0 op_sel_hi:[1,0]
	v_pk_fma_f32 v[52:53], v[52:53], v[150:151], v[134:135]
	v_pk_fma_f32 v[50:51], v[50:51], v[148:149], v[132:133]
	s_nop 0
	v_cvt_pk_bf16_f32 v50, v50, v51
	v_cvt_pk_bf16_f32 v51, v52, v53
	global_store_dwordx2 v[88:89], v[50:51], off offset:1536
	s_andn2_b64 vcc, exec, s[10:11]
	s_cbranch_vccnz .LBB0_162
	s_and_b64 vcc, exec, s[38:39]
	s_cbranch_vccnz .LBB0_172
	v_mov_b32_e32 v50, v47
	v_mov_b32_e32 v51, v48
	v_mov_b32_e32 v52, v46
	v_mov_b32_e32 v53, v49
	v_pk_add_f32 v[50:51], v[50:51], v[52:53]
	v_mov_b32_e32 v52, v43
	v_mov_b32_e32 v53, v44
	v_mov_b32_e32 v54, v42
	v_mov_b32_e32 v55, v45
	v_pk_add_f32 v[52:53], v[52:53], v[54:55]
	v_add_f32_e32 v50, v50, v51
	v_pk_add_f32 v[52:53], v[52:53], v[52:53] op_sel:[0,1] op_sel_hi:[1,0]
	v_add_f32_e32 v50, 0, v50
	v_add_f32_e32 v54, v38, v39
	v_add_f32_e32 v56, v40, v41
	v_mov_b32_e32 v51, v34
	v_mov_b32_e32 v53, v35
	v_mov_b32_e32 v55, v36
	v_mov_b32_e32 v57, v37
	v_pk_add_f32 v[50:51], v[50:51], v[52:53]
	v_pk_add_f32 v[52:53], v[54:55], v[56:57]
	s_nop 0
	v_pk_add_f32 v[50:51], v[50:51], v[52:53]
	v_xor_b32_e32 v52, 1, v211
	v_add_f32_e32 v50, v50, v51
	v_and_b32_e32 v51, 64, v211
	v_add_u32_e32 v51, 64, v51
	v_cmp_lt_i32_e32 vcc, v52, v51
	s_nop 1
	v_cndmask_b32_e32 v52, v211, v52, vcc
	v_lshlrev_b32_e32 v52, 2, v52
	ds_bpermute_b32 v53, v52, v50
	s_waitcnt lgkmcnt(0)
	v_add_f32_e32 v50, v50, v53
	v_xor_b32_e32 v53, 2, v211
	v_cmp_lt_i32_e32 vcc, v53, v51
	s_nop 1
	v_cndmask_b32_e32 v53, v211, v53, vcc
	v_lshlrev_b32_e32 v53, 2, v53
	ds_bpermute_b32 v54, v53, v50
	s_waitcnt lgkmcnt(0)
	v_add_f32_e32 v50, v50, v54
	v_xor_b32_e32 v54, 4, v211
	v_cmp_lt_i32_e32 vcc, v54, v51
	s_nop 1
	v_cndmask_b32_e32 v54, v211, v54, vcc
	v_lshlrev_b32_e32 v54, 2, v54
	ds_bpermute_b32 v55, v54, v50
	s_waitcnt lgkmcnt(0)
	v_add_f32_e32 v50, v50, v55
	v_xor_b32_e32 v55, 8, v211
	v_cmp_lt_i32_e32 vcc, v55, v51
	s_nop 1
	v_cndmask_b32_e32 v55, v211, v55, vcc
	v_lshlrev_b32_e32 v55, 2, v55
	ds_bpermute_b32 v56, v55, v50
	s_waitcnt lgkmcnt(0)
	v_add_f32_e32 v50, v50, v56
	v_xor_b32_e32 v56, 16, v211
	v_cmp_lt_i32_e32 vcc, v56, v51
	s_nop 1
	v_cndmask_b32_e32 v56, v211, v56, vcc
	v_lshlrev_b32_e32 v56, 2, v56
	ds_bpermute_b32 v57, v56, v50
	s_waitcnt lgkmcnt(0)
	v_add_f32_e32 v50, v50, v57
	v_xor_b32_e32 v57, 32, v211
	v_cmp_lt_i32_e32 vcc, v57, v51
	s_nop 1
	v_cndmask_b32_e32 v51, v211, v57, vcc
	v_lshlrev_b32_e32 v57, 2, v51
	ds_bpermute_b32 v51, v57, v50
	s_waitcnt lgkmcnt(0)
	v_add_f32_e32 v51, v50, v51
	v_fmamk_f32 v49, v51, 0xba800000, v49
	v_fmamk_f32 v47, v51, 0xba800000, v47
	v_fmamk_f32 v48, v51, 0xba800000, v48
	v_fmac_f32_e32 v46, 0xba800000, v51
	v_mul_f32_e32 v50, v47, v47
	v_mul_f32_e32 v58, v49, v49
	v_fmac_f32_e32 v50, v46, v46
	v_fmac_f32_e32 v58, v48, v48
	v_fmamk_f32 v45, v51, 0xba800000, v45
	v_fmamk_f32 v43, v51, 0xba800000, v43
	v_add_f32_e32 v50, v50, v58
	v_fmamk_f32 v44, v51, 0xba800000, v44
	v_fmac_f32_e32 v42, 0xba800000, v51
	v_mul_f32_e32 v58, v43, v43
	v_mul_f32_e32 v59, v45, v45
	v_fmac_f32_e32 v58, v42, v42
	v_fmac_f32_e32 v59, v44, v44
	v_add_f32_e32 v58, v58, v59
	v_fmamk_f32 v41, v51, 0xba800000, v41
	v_fmamk_f32 v39, v51, 0xba800000, v39
	v_add_f32_e32 v50, v50, v58
	v_fmamk_f32 v40, v51, 0xba800000, v40
	v_fmac_f32_e32 v38, 0xba800000, v51
	v_mul_f32_e32 v58, v39, v39
	v_mul_f32_e32 v59, v41, v41
	v_fmac_f32_e32 v58, v38, v38
	v_fmac_f32_e32 v59, v40, v40
	v_add_f32_e32 v58, v58, v59
	v_fmamk_f32 v37, v51, 0xba800000, v37
	v_fmamk_f32 v35, v51, 0xba800000, v35
	v_add_f32_e32 v50, v50, v58
	v_fmamk_f32 v36, v51, 0xba800000, v36
	v_fmac_f32_e32 v34, 0xba800000, v51
	v_mul_f32_e32 v58, v35, v35
	v_mul_f32_e32 v59, v37, v37
	v_fmac_f32_e32 v58, v34, v34
	v_fmac_f32_e32 v59, v36, v36
	v_add_f32_e32 v58, v58, v59
	v_add_f32_e32 v50, v50, v58
	ds_bpermute_b32 v52, v52, v50
	s_waitcnt lgkmcnt(0)
	v_add_f32_e32 v50, v50, v52
	ds_bpermute_b32 v52, v53, v50
	s_waitcnt lgkmcnt(0)
	v_add_f32_e32 v50, v50, v52
	ds_bpermute_b32 v52, v54, v50
	s_waitcnt lgkmcnt(0)
	v_add_f32_e32 v50, v50, v52
	ds_bpermute_b32 v52, v55, v50
	s_waitcnt lgkmcnt(0)
	v_add_f32_e32 v50, v50, v52
	ds_bpermute_b32 v52, v56, v50
	s_waitcnt lgkmcnt(0)
	v_add_f32_e32 v50, v50, v52
	ds_bpermute_b32 v52, v57, v50
	s_waitcnt lgkmcnt(0)
	v_add_f32_e32 v50, v50, v52
	v_fmamk_f32 v50, v50, 0x3a800000, v213
	v_mul_f32_e32 v52, 0x4f800000, v50
	v_cmp_gt_f32_e32 vcc, s61, v50
	s_nop 1
	v_cndmask_b32_e32 v50, v50, v52, vcc
	v_sqrt_f32_e32 v52, v50
	s_nop 0
	v_add_u32_e32 v53, -1, v52
	v_fma_f32 v54, -v53, v52, v50
	v_cmp_ge_f32_e64 s[0:1], 0, v54
	v_add_u32_e32 v54, 1, v52
	s_nop 0
	v_cndmask_b32_e64 v53, v52, v53, s[0:1]
	v_fma_f32 v52, -v54, v52, v50
	v_cmp_lt_f32_e64 s[0:1], 0, v52
	s_nop 1
	v_cndmask_b32_e64 v52, v53, v54, s[0:1]
	v_mul_f32_e32 v53, 0x37800000, v52
	v_cndmask_b32_e32 v52, v52, v53, vcc
	v_cmp_class_f32_e32 vcc, v50, v214
	s_nop 1
	v_cndmask_b32_e32 v50, v52, v50, vcc
	v_div_scale_f32 v52, s[0:1], v50, v50, 1.0
	v_rcp_f32_e32 v53, v52
	s_nop 0
	v_fma_f32 v54, -v52, v53, 1.0
	v_fmac_f32_e32 v53, v54, v53
	v_div_scale_f32 v54, vcc, 1.0, v50, 1.0
	v_mul_f32_e32 v55, v54, v53
	v_fma_f32 v56, -v52, v55, v54
	v_fmac_f32_e32 v55, v56, v53
	v_fma_f32 v52, -v52, v55, v54
	v_div_fmas_f32 v52, v52, v53, v55
	v_div_fixup_f32 v50, v52, v50, 1.0
	s_and_saveexec_b64 s[0:1], s[36:37]
	s_cbranch_execz .LBB0_171
	s_add_u32 s10, s90, s34
	v_mul_f32_e32 v52, 0x3a800000, v51
	s_addc_u32 s11, s91, s35
	v_mov_b32_e32 v53, v50
	global_store_dwordx2 v1, v[52:53], s[10:11]
.LBB0_171:
	s_or_b64 exec, exec, s[0:1]
	v_pk_mul_f32 v[48:49], v[50:51], v[48:49] op_sel_hi:[0,1]
	v_pk_mul_f32 v[46:47], v[50:51], v[46:47] op_sel_hi:[0,1]
	v_pk_mul_f32 v[44:45], v[50:51], v[44:45] op_sel_hi:[0,1]
	v_pk_mul_f32 v[42:43], v[50:51], v[42:43] op_sel_hi:[0,1]
	v_pk_mul_f32 v[40:41], v[50:51], v[40:41] op_sel_hi:[0,1]
	v_pk_mul_f32 v[38:39], v[50:51], v[38:39] op_sel_hi:[0,1]
	v_pk_mul_f32 v[36:37], v[50:51], v[36:37] op_sel_hi:[0,1]
	v_pk_mul_f32 v[34:35], v[50:51], v[34:35] op_sel_hi:[0,1]
	v_pk_fma_f32 v[48:49], v[154:155], v[48:49], v[170:171]
	v_pk_fma_f32 v[46:47], v[152:153], v[46:47], v[168:169]
	v_pk_fma_f32 v[44:45], v[158:159], v[44:45], v[174:175]
	v_pk_fma_f32 v[42:43], v[156:157], v[42:43], v[172:173]
	v_pk_fma_f32 v[40:41], v[162:163], v[40:41], v[178:179]
	v_pk_fma_f32 v[38:39], v[160:161], v[38:39], v[176:177]
	v_pk_fma_f32 v[36:37], v[166:167], v[36:37], v[182:183]
	v_pk_fma_f32 v[34:35], v[164:165], v[34:35], v[180:181]
.LBB0_172:
	s_min_i32 s0, s49, 0x8000
	s_ashr_i32 s0, s0, 12
	s_mulk_i32 s0, 0xc00
	s_ashr_i32 s1, s0, 31
	s_lshl_b64 s[0:1], s[0:1], 2
	s_add_u32 s0, s19, s0
	s_addc_u32 s1, s28, s1
	s_add_u32 s16, s0, 0x1000
	s_addc_u32 s17, s1, 0
	global_load_dwordx4 v[120:123], v0, s[0:1]
	global_load_dwordx4 v[124:127], v0, s[0:1] offset:1024
	global_load_dwordx4 v[128:131], v0, s[0:1] offset:2048
	global_load_dwordx4 v[132:135], v0, s[0:1] offset:3072
	global_load_dwordx4 v[136:139], v0, s[16:17]
	global_load_dwordx4 v[140:143], v0, s[16:17] offset:1024
	global_load_dwordx4 v[144:147], v0, s[16:17] offset:2048
	global_load_dwordx4 v[148:151], v0, s[16:17] offset:3072
	v_lshl_add_u64 v[60:61], s[90:91], 0, v[76:77]
	v_add_co_u32_e32 v60, vcc, s70, v60
	v_addc_co_u32_e32 v61, vcc, 0, v61, vcc
	s_waitcnt vmcnt(0)
	v_pk_add_f32 v[138:139], v[138:139], 1.0 op_sel_hi:[1,0]
	v_pk_add_f32 v[136:137], v[136:137], 1.0 op_sel_hi:[1,0]
	v_pk_fma_f32 v[48:49], v[48:49], v[138:139], v[122:123]
	v_pk_fma_f32 v[46:47], v[46:47], v[136:137], v[120:121]
	s_nop 0
	v_cvt_pk_bf16_f32 v46, v46, v47
	v_cvt_pk_bf16_f32 v47, v48, v49
	global_store_dwordx2 v[60:61], v[46:47], off
	v_pk_add_f32 v[142:143], v[142:143], 1.0 op_sel_hi:[1,0]
	v_pk_add_f32 v[140:141], v[140:141], 1.0 op_sel_hi:[1,0]
	v_pk_fma_f32 v[44:45], v[44:45], v[142:143], v[126:127]
	v_pk_fma_f32 v[42:43], v[42:43], v[140:141], v[124:125]
	s_nop 0
	v_cvt_pk_bf16_f32 v42, v42, v43
	v_cvt_pk_bf16_f32 v43, v44, v45
	global_store_dwordx2 v[60:61], v[42:43], off offset:512
	v_pk_add_f32 v[146:147], v[146:147], 1.0 op_sel_hi:[1,0]
	v_pk_add_f32 v[144:145], v[144:145], 1.0 op_sel_hi:[1,0]
	v_pk_fma_f32 v[40:41], v[40:41], v[146:147], v[130:131]
	v_pk_fma_f32 v[38:39], v[38:39], v[144:145], v[128:129]
	s_nop 0
	v_cvt_pk_bf16_f32 v38, v38, v39
	v_cvt_pk_bf16_f32 v39, v40, v41
	global_store_dwordx2 v[60:61], v[38:39], off offset:1024
	v_pk_add_f32 v[150:151], v[150:151], 1.0 op_sel_hi:[1,0]
	v_pk_add_f32 v[148:149], v[148:149], 1.0 op_sel_hi:[1,0]
	v_pk_fma_f32 v[36:37], v[36:37], v[150:151], v[134:135]
	v_pk_fma_f32 v[34:35], v[34:35], v[148:149], v[132:133]
	s_nop 0
	v_cvt_pk_bf16_f32 v34, v34, v35
	v_cvt_pk_bf16_f32 v35, v36, v37
	global_store_dwordx2 v[60:61], v[34:35], off offset:1536
	s_andn2_b64 vcc, exec, s[50:51]
	s_cbranch_vccnz .LBB0_162
	s_and_b64 vcc, exec, s[38:39]
	s_add_i32 s10, s31, s46
	s_cbranch_vccnz .LBB0_177
	v_mov_b32_e32 v34, v31
	v_mov_b32_e32 v35, v32
	v_mov_b32_e32 v36, v30
	v_mov_b32_e32 v37, v33
	v_pk_add_f32 v[34:35], v[34:35], v[36:37]
	v_mov_b32_e32 v36, v27
	v_mov_b32_e32 v37, v28
	v_mov_b32_e32 v38, v26
	v_mov_b32_e32 v39, v29
	v_pk_add_f32 v[36:37], v[36:37], v[38:39]
	v_add_f32_e32 v34, v34, v35
	v_pk_add_f32 v[36:37], v[36:37], v[36:37] op_sel:[0,1] op_sel_hi:[1,0]
	v_add_f32_e32 v34, 0, v34
	v_add_f32_e32 v38, v18, v19
	v_add_f32_e32 v40, v20, v21
	v_mov_b32_e32 v35, v22
	v_mov_b32_e32 v37, v23
	v_mov_b32_e32 v39, v24
	v_mov_b32_e32 v41, v25
	v_pk_add_f32 v[34:35], v[34:35], v[36:37]
	v_pk_add_f32 v[36:37], v[38:39], v[40:41]
	s_nop 0
	v_pk_add_f32 v[34:35], v[34:35], v[36:37]
	v_xor_b32_e32 v36, 1, v211
	v_add_f32_e32 v34, v34, v35
	v_and_b32_e32 v35, 64, v211
	v_add_u32_e32 v35, 64, v35
	v_cmp_lt_i32_e32 vcc, v36, v35
	s_nop 1
	v_cndmask_b32_e32 v36, v211, v36, vcc
	v_lshlrev_b32_e32 v36, 2, v36
	ds_bpermute_b32 v37, v36, v34
	s_waitcnt lgkmcnt(0)
	v_add_f32_e32 v34, v34, v37
	v_xor_b32_e32 v37, 2, v211
	v_cmp_lt_i32_e32 vcc, v37, v35
	s_nop 1
	v_cndmask_b32_e32 v37, v211, v37, vcc
	v_lshlrev_b32_e32 v37, 2, v37
	ds_bpermute_b32 v38, v37, v34
	s_waitcnt lgkmcnt(0)
	v_add_f32_e32 v34, v34, v38
	v_xor_b32_e32 v38, 4, v211
	v_cmp_lt_i32_e32 vcc, v38, v35
	s_nop 1
	v_cndmask_b32_e32 v38, v211, v38, vcc
	v_lshlrev_b32_e32 v38, 2, v38
	ds_bpermute_b32 v39, v38, v34
	s_waitcnt lgkmcnt(0)
	v_add_f32_e32 v34, v34, v39
	v_xor_b32_e32 v39, 8, v211
	v_cmp_lt_i32_e32 vcc, v39, v35
	s_nop 1
	v_cndmask_b32_e32 v39, v211, v39, vcc
	v_lshlrev_b32_e32 v39, 2, v39
	ds_bpermute_b32 v40, v39, v34
	s_waitcnt lgkmcnt(0)
	v_add_f32_e32 v34, v34, v40
	v_xor_b32_e32 v40, 16, v211
	v_cmp_lt_i32_e32 vcc, v40, v35
	s_nop 1
	v_cndmask_b32_e32 v40, v211, v40, vcc
	v_lshlrev_b32_e32 v40, 2, v40
	ds_bpermute_b32 v41, v40, v34
	s_waitcnt lgkmcnt(0)
	v_add_f32_e32 v34, v34, v41
	v_xor_b32_e32 v41, 32, v211
	v_cmp_lt_i32_e32 vcc, v41, v35
	s_nop 1
	v_cndmask_b32_e32 v35, v211, v41, vcc
	v_lshlrev_b32_e32 v41, 2, v35
	ds_bpermute_b32 v35, v41, v34
	s_waitcnt lgkmcnt(0)
	v_add_f32_e32 v35, v34, v35
	v_fmamk_f32 v33, v35, 0xba800000, v33
	v_fmamk_f32 v31, v35, 0xba800000, v31
	v_fmamk_f32 v32, v35, 0xba800000, v32
	v_fmac_f32_e32 v30, 0xba800000, v35
	v_mul_f32_e32 v34, v31, v31
	v_mul_f32_e32 v42, v33, v33
	v_fmac_f32_e32 v34, v30, v30
	v_fmac_f32_e32 v42, v32, v32
	v_fmamk_f32 v29, v35, 0xba800000, v29
	v_fmamk_f32 v27, v35, 0xba800000, v27
	v_add_f32_e32 v34, v34, v42
	v_fmamk_f32 v28, v35, 0xba800000, v28
	v_fmac_f32_e32 v26, 0xba800000, v35
	v_mul_f32_e32 v42, v27, v27
	v_mul_f32_e32 v43, v29, v29
	v_fmac_f32_e32 v42, v26, v26
	v_fmac_f32_e32 v43, v28, v28
	v_add_f32_e32 v42, v42, v43
	v_fmamk_f32 v21, v35, 0xba800000, v21
	v_fmamk_f32 v19, v35, 0xba800000, v19
	v_add_f32_e32 v34, v34, v42
	v_fmamk_f32 v20, v35, 0xba800000, v20
	v_fmac_f32_e32 v18, 0xba800000, v35
	v_mul_f32_e32 v42, v19, v19
	v_mul_f32_e32 v43, v21, v21
	v_fmac_f32_e32 v42, v18, v18
	v_fmac_f32_e32 v43, v20, v20
	v_add_f32_e32 v42, v42, v43
	v_fmamk_f32 v25, v35, 0xba800000, v25
	v_fmamk_f32 v23, v35, 0xba800000, v23
	v_add_f32_e32 v34, v34, v42
	v_fmamk_f32 v24, v35, 0xba800000, v24
	v_fmac_f32_e32 v22, 0xba800000, v35
	v_mul_f32_e32 v42, v23, v23
	v_mul_f32_e32 v43, v25, v25
	v_fmac_f32_e32 v42, v22, v22
	v_fmac_f32_e32 v43, v24, v24
	v_add_f32_e32 v42, v42, v43
	v_add_f32_e32 v34, v34, v42
	ds_bpermute_b32 v36, v36, v34
	s_waitcnt lgkmcnt(0)
	v_add_f32_e32 v34, v34, v36
	ds_bpermute_b32 v36, v37, v34
	s_waitcnt lgkmcnt(0)
	v_add_f32_e32 v34, v34, v36
	ds_bpermute_b32 v36, v38, v34
	s_waitcnt lgkmcnt(0)
	v_add_f32_e32 v34, v34, v36
	ds_bpermute_b32 v36, v39, v34
	s_waitcnt lgkmcnt(0)
	v_add_f32_e32 v34, v34, v36
	ds_bpermute_b32 v36, v40, v34
	s_waitcnt lgkmcnt(0)
	v_add_f32_e32 v34, v34, v36
	ds_bpermute_b32 v36, v41, v34
	s_waitcnt lgkmcnt(0)
	v_add_f32_e32 v34, v34, v36
	v_fmamk_f32 v34, v34, 0x3a800000, v213
	v_mul_f32_e32 v36, 0x4f800000, v34
	v_cmp_gt_f32_e32 vcc, s61, v34
	s_nop 1
	v_cndmask_b32_e32 v34, v34, v36, vcc
	v_sqrt_f32_e32 v36, v34
	s_nop 0
	v_add_u32_e32 v37, -1, v36
	v_fma_f32 v38, -v37, v36, v34
	v_cmp_ge_f32_e64 s[0:1], 0, v38
	v_add_u32_e32 v38, 1, v36
	s_nop 0
	v_cndmask_b32_e64 v37, v36, v37, s[0:1]
	v_fma_f32 v36, -v38, v36, v34
	v_cmp_lt_f32_e64 s[0:1], 0, v36
	s_nop 1
	v_cndmask_b32_e64 v36, v37, v38, s[0:1]
	v_mul_f32_e32 v37, 0x37800000, v36
	v_cndmask_b32_e32 v36, v36, v37, vcc
	v_cmp_class_f32_e32 vcc, v34, v214
	s_nop 1
	v_cndmask_b32_e32 v34, v36, v34, vcc
	v_div_scale_f32 v36, s[0:1], v34, v34, 1.0
	v_rcp_f32_e32 v37, v36
	s_nop 0
	v_fma_f32 v38, -v36, v37, 1.0
	v_fmac_f32_e32 v37, v38, v37
	v_div_scale_f32 v38, vcc, 1.0, v34, 1.0
	v_mul_f32_e32 v39, v38, v37
	v_fma_f32 v40, -v36, v39, v38
	v_fmac_f32_e32 v39, v40, v37
	v_fma_f32 v36, -v36, v39, v38
	v_div_fmas_f32 v36, v36, v37, v39
	v_div_fixup_f32 v34, v36, v34, 1.0
	s_and_saveexec_b64 s[0:1], s[36:37]
	s_cbranch_execz .LBB0_176
	s_ashr_i32 s11, s10, 31
	s_lshl_b64 s[50:51], s[10:11], 3
	v_readlane_b32 s11, v252, 20
	s_add_u32 s50, s11, s50
	v_readlane_b32 s11, v252, 21
	v_mul_f32_e32 v36, 0x3a800000, v35
	s_addc_u32 s51, s11, s51
	v_mov_b32_e32 v37, v34
	global_store_dwordx2 v1, v[36:37], s[50:51]
.LBB0_176:
	s_or_b64 exec, exec, s[0:1]
	v_pk_mul_f32 v[32:33], v[34:35], v[32:33] op_sel_hi:[0,1]
	v_pk_mul_f32 v[30:31], v[34:35], v[30:31] op_sel_hi:[0,1]
	v_pk_mul_f32 v[28:29], v[34:35], v[28:29] op_sel_hi:[0,1]
	v_pk_mul_f32 v[26:27], v[34:35], v[26:27] op_sel_hi:[0,1]
	v_pk_mul_f32 v[20:21], v[34:35], v[20:21] op_sel_hi:[0,1]
	v_pk_mul_f32 v[18:19], v[34:35], v[18:19] op_sel_hi:[0,1]
	v_pk_mul_f32 v[24:25], v[34:35], v[24:25] op_sel_hi:[0,1]
	v_pk_mul_f32 v[22:23], v[34:35], v[22:23] op_sel_hi:[0,1]
	v_pk_fma_f32 v[32:33], v[154:155], v[32:33], v[170:171]
	v_pk_fma_f32 v[30:31], v[152:153], v[30:31], v[168:169]
	v_pk_fma_f32 v[28:29], v[158:159], v[28:29], v[174:175]
	v_pk_fma_f32 v[26:27], v[156:157], v[26:27], v[172:173]
	v_pk_fma_f32 v[20:21], v[162:163], v[20:21], v[178:179]
	v_pk_fma_f32 v[18:19], v[160:161], v[18:19], v[176:177]
	v_pk_fma_f32 v[24:25], v[166:167], v[24:25], v[182:183]
	v_pk_fma_f32 v[22:23], v[164:165], v[22:23], v[180:181]
.LBB0_177:
	s_min_i32 s0, s10, 0x8000
	s_ashr_i32 s0, s0, 12
	s_mulk_i32 s0, 0xc00
	s_ashr_i32 s1, s0, 31
	s_lshl_b64 s[0:1], s[0:1], 2
	s_add_u32 s0, s19, s0
	s_addc_u32 s1, s28, s1
	s_add_u32 s16, s0, 0x1000
	s_addc_u32 s17, s1, 0
	global_load_dwordx4 v[120:123], v0, s[0:1]
	global_load_dwordx4 v[124:127], v0, s[0:1] offset:1024
	global_load_dwordx4 v[128:131], v0, s[0:1] offset:2048
	global_load_dwordx4 v[132:135], v0, s[0:1] offset:3072
	global_load_dwordx4 v[136:139], v0, s[16:17]
	global_load_dwordx4 v[140:143], v0, s[16:17] offset:1024
	global_load_dwordx4 v[144:147], v0, s[16:17] offset:2048
	global_load_dwordx4 v[148:151], v0, s[16:17] offset:3072
	s_ashr_i32 s11, s10, 31
	s_lshl_b64 s[10:11], s[10:11], 11
	v_lshl_add_u64 v[42:43], v[72:73], 0, s[10:11]
	s_waitcnt vmcnt(0)
	v_pk_add_f32 v[138:139], v[138:139], 1.0 op_sel_hi:[1,0]
	v_pk_add_f32 v[136:137], v[136:137], 1.0 op_sel_hi:[1,0]
	v_pk_fma_f32 v[32:33], v[32:33], v[138:139], v[122:123]
	v_pk_fma_f32 v[30:31], v[30:31], v[136:137], v[120:121]
	s_nop 0
	v_cvt_pk_bf16_f32 v30, v30, v31
	v_cvt_pk_bf16_f32 v31, v32, v33
	global_store_dwordx2 v[42:43], v[30:31], off
	v_pk_add_f32 v[142:143], v[142:143], 1.0 op_sel_hi:[1,0]
	v_pk_add_f32 v[140:141], v[140:141], 1.0 op_sel_hi:[1,0]
	v_pk_fma_f32 v[28:29], v[28:29], v[142:143], v[126:127]
	v_pk_fma_f32 v[26:27], v[26:27], v[140:141], v[124:125]
	s_nop 0
	v_cvt_pk_bf16_f32 v26, v26, v27
	v_cvt_pk_bf16_f32 v27, v28, v29
	global_store_dwordx2 v[42:43], v[26:27], off offset:512
	v_pk_add_f32 v[146:147], v[146:147], 1.0 op_sel_hi:[1,0]
	v_pk_add_f32 v[144:145], v[144:145], 1.0 op_sel_hi:[1,0]
	v_pk_fma_f32 v[20:21], v[20:21], v[146:147], v[130:131]
	v_pk_fma_f32 v[18:19], v[18:19], v[144:145], v[128:129]
	s_nop 0
	v_cvt_pk_bf16_f32 v18, v18, v19
	v_cvt_pk_bf16_f32 v19, v20, v21
	global_store_dwordx2 v[42:43], v[18:19], off offset:1024
	v_pk_add_f32 v[150:151], v[150:151], 1.0 op_sel_hi:[1,0]
	v_pk_add_f32 v[148:149], v[148:149], 1.0 op_sel_hi:[1,0]
	v_pk_fma_f32 v[24:25], v[24:25], v[150:151], v[134:135]
	v_pk_fma_f32 v[22:23], v[22:23], v[148:149], v[132:133]
	s_nop 0
	v_cvt_pk_bf16_f32 v22, v22, v23
	v_cvt_pk_bf16_f32 v23, v24, v25
	global_store_dwordx2 v[42:43], v[22:23], off offset:1536
	s_andn2_b64 vcc, exec, s[8:9]
	s_cbranch_vccnz .LBB0_162
	s_mul_i32 s0, s12, 3
	s_and_b64 vcc, exec, s[38:39]
	s_add_i32 s8, s0, s46
	s_cbranch_vccnz .LBB0_161
	v_mov_b32_e32 v18, v15
	v_mov_b32_e32 v19, v16
	v_mov_b32_e32 v20, v14
	v_mov_b32_e32 v21, v17
	v_pk_add_f32 v[18:19], v[18:19], v[20:21]
	v_mov_b32_e32 v20, v11
	v_mov_b32_e32 v21, v12
	v_mov_b32_e32 v22, v10
	v_mov_b32_e32 v23, v13
	v_pk_add_f32 v[20:21], v[20:21], v[22:23]
	v_add_f32_e32 v18, v18, v19
	v_pk_add_f32 v[20:21], v[20:21], v[20:21] op_sel:[0,1] op_sel_hi:[1,0]
	v_add_f32_e32 v18, 0, v18
	v_add_f32_e32 v22, v2, v3
	v_add_f32_e32 v24, v4, v5
	v_mov_b32_e32 v19, v6
	v_mov_b32_e32 v21, v7
	v_mov_b32_e32 v23, v8
	v_mov_b32_e32 v25, v9
	v_pk_add_f32 v[18:19], v[18:19], v[20:21]
	v_pk_add_f32 v[20:21], v[22:23], v[24:25]
	s_nop 0
	v_pk_add_f32 v[18:19], v[18:19], v[20:21]
	v_xor_b32_e32 v20, 1, v211
	v_add_f32_e32 v18, v18, v19
	v_and_b32_e32 v19, 64, v211
	v_add_u32_e32 v19, 64, v19
	v_cmp_lt_i32_e32 vcc, v20, v19
	s_nop 1
	v_cndmask_b32_e32 v20, v211, v20, vcc
	v_lshlrev_b32_e32 v20, 2, v20
	ds_bpermute_b32 v21, v20, v18
	s_waitcnt lgkmcnt(0)
	v_add_f32_e32 v18, v18, v21
	v_xor_b32_e32 v21, 2, v211
	v_cmp_lt_i32_e32 vcc, v21, v19
	s_nop 1
	v_cndmask_b32_e32 v21, v211, v21, vcc
	v_lshlrev_b32_e32 v21, 2, v21
	ds_bpermute_b32 v22, v21, v18
	s_waitcnt lgkmcnt(0)
	v_add_f32_e32 v18, v18, v22
	v_xor_b32_e32 v22, 4, v211
	v_cmp_lt_i32_e32 vcc, v22, v19
	s_nop 1
	v_cndmask_b32_e32 v22, v211, v22, vcc
	v_lshlrev_b32_e32 v22, 2, v22
	ds_bpermute_b32 v23, v22, v18
	s_waitcnt lgkmcnt(0)
	v_add_f32_e32 v18, v18, v23
	v_xor_b32_e32 v23, 8, v211
	v_cmp_lt_i32_e32 vcc, v23, v19
	s_nop 1
	v_cndmask_b32_e32 v23, v211, v23, vcc
	v_lshlrev_b32_e32 v23, 2, v23
	ds_bpermute_b32 v24, v23, v18
	s_waitcnt lgkmcnt(0)
	v_add_f32_e32 v18, v18, v24
	v_xor_b32_e32 v24, 16, v211
	v_cmp_lt_i32_e32 vcc, v24, v19
	s_nop 1
	v_cndmask_b32_e32 v24, v211, v24, vcc
	v_lshlrev_b32_e32 v24, 2, v24
	ds_bpermute_b32 v25, v24, v18
	s_waitcnt lgkmcnt(0)
	v_add_f32_e32 v18, v18, v25
	v_xor_b32_e32 v25, 32, v211
	v_cmp_lt_i32_e32 vcc, v25, v19
	s_nop 1
	v_cndmask_b32_e32 v19, v211, v25, vcc
	v_lshlrev_b32_e32 v25, 2, v19
	ds_bpermute_b32 v19, v25, v18
	s_waitcnt lgkmcnt(0)
	v_add_f32_e32 v19, v18, v19
	v_fmamk_f32 v17, v19, 0xba800000, v17
	v_fmamk_f32 v15, v19, 0xba800000, v15
	v_fmamk_f32 v16, v19, 0xba800000, v16
	v_fmac_f32_e32 v14, 0xba800000, v19
	v_mul_f32_e32 v18, v15, v15
	v_mul_f32_e32 v26, v17, v17
	v_fmac_f32_e32 v18, v14, v14
	v_fmac_f32_e32 v26, v16, v16
	v_fmamk_f32 v13, v19, 0xba800000, v13
	v_fmamk_f32 v11, v19, 0xba800000, v11
	v_add_f32_e32 v18, v18, v26
	v_fmamk_f32 v12, v19, 0xba800000, v12
	v_fmac_f32_e32 v10, 0xba800000, v19
	v_mul_f32_e32 v26, v11, v11
	v_mul_f32_e32 v27, v13, v13
	v_fmac_f32_e32 v26, v10, v10
	v_fmac_f32_e32 v27, v12, v12
	v_add_f32_e32 v26, v26, v27
	v_fmamk_f32 v5, v19, 0xba800000, v5
	v_fmamk_f32 v3, v19, 0xba800000, v3
	v_add_f32_e32 v18, v18, v26
	v_fmamk_f32 v4, v19, 0xba800000, v4
	v_fmac_f32_e32 v2, 0xba800000, v19
	v_mul_f32_e32 v26, v3, v3
	v_mul_f32_e32 v27, v5, v5
	v_fmac_f32_e32 v26, v2, v2
	v_fmac_f32_e32 v27, v4, v4
	v_add_f32_e32 v26, v26, v27
	v_fmamk_f32 v9, v19, 0xba800000, v9
	v_fmamk_f32 v7, v19, 0xba800000, v7
	v_add_f32_e32 v18, v18, v26
	v_fmamk_f32 v8, v19, 0xba800000, v8
	v_fmac_f32_e32 v6, 0xba800000, v19
	v_mul_f32_e32 v26, v7, v7
	v_mul_f32_e32 v27, v9, v9
	v_fmac_f32_e32 v26, v6, v6
	v_fmac_f32_e32 v27, v8, v8
	v_add_f32_e32 v26, v26, v27
	v_add_f32_e32 v18, v18, v26
	ds_bpermute_b32 v20, v20, v18
	s_waitcnt lgkmcnt(0)
	v_add_f32_e32 v18, v18, v20
	ds_bpermute_b32 v20, v21, v18
	s_waitcnt lgkmcnt(0)
	v_add_f32_e32 v18, v18, v20
	ds_bpermute_b32 v20, v22, v18
	s_waitcnt lgkmcnt(0)
	v_add_f32_e32 v18, v18, v20
	ds_bpermute_b32 v20, v23, v18
	s_waitcnt lgkmcnt(0)
	v_add_f32_e32 v18, v18, v20
	ds_bpermute_b32 v20, v24, v18
	s_waitcnt lgkmcnt(0)
	v_add_f32_e32 v18, v18, v20
	ds_bpermute_b32 v20, v25, v18
	s_waitcnt lgkmcnt(0)
	v_add_f32_e32 v18, v18, v20
	v_fmamk_f32 v18, v18, 0x3a800000, v213
	v_mul_f32_e32 v20, 0x4f800000, v18
	v_cmp_gt_f32_e32 vcc, s61, v18
	s_nop 1
	v_cndmask_b32_e32 v18, v18, v20, vcc
	v_sqrt_f32_e32 v20, v18
	s_nop 0
	v_add_u32_e32 v21, -1, v20
	v_fma_f32 v22, -v21, v20, v18
	v_cmp_ge_f32_e64 s[0:1], 0, v22
	v_add_u32_e32 v22, 1, v20
	s_nop 0
	v_cndmask_b32_e64 v21, v20, v21, s[0:1]
	v_fma_f32 v20, -v22, v20, v18
	v_cmp_lt_f32_e64 s[0:1], 0, v20
	s_nop 1
	v_cndmask_b32_e64 v20, v21, v22, s[0:1]
	v_mul_f32_e32 v21, 0x37800000, v20
	v_cndmask_b32_e32 v20, v20, v21, vcc
	v_cmp_class_f32_e32 vcc, v18, v214
	s_nop 1
	v_cndmask_b32_e32 v18, v20, v18, vcc
	v_div_scale_f32 v20, s[0:1], v18, v18, 1.0
	v_rcp_f32_e32 v21, v20
	s_nop 0
	v_fma_f32 v22, -v20, v21, 1.0
	v_fmac_f32_e32 v21, v22, v21
	v_div_scale_f32 v22, vcc, 1.0, v18, 1.0
	v_mul_f32_e32 v23, v22, v21
	v_fma_f32 v24, -v20, v23, v22
	v_fmac_f32_e32 v23, v24, v21
	v_fma_f32 v20, -v20, v23, v22
	v_div_fmas_f32 v20, v20, v21, v23
	v_div_fixup_f32 v18, v20, v18, 1.0
	s_and_saveexec_b64 s[0:1], s[36:37]
	s_cbranch_execz .LBB0_160
	s_ashr_i32 s9, s8, 31
	s_lshl_b64 s[10:11], s[8:9], 3
	v_readlane_b32 s9, v252, 20
	s_add_u32 s10, s9, s10
	v_readlane_b32 s9, v252, 21
	v_mul_f32_e32 v20, 0x3a800000, v19
	s_addc_u32 s11, s9, s11
	v_mov_b32_e32 v21, v18
	global_store_dwordx2 v1, v[20:21], s[10:11]
	s_branch .LBB0_160

.LBB0_556:
	s_nop 7
	v_div_scale_f32 v2, s[0:1], v50, v50, 1.0
	v_rcp_f32_e32 v3, v2
	v_readlane_b32 s0, v254, 4
	v_lshlrev_b32_e32 v8, 4, v130
	s_waitcnt vmcnt(0) lgkmcnt(0)
	s_barrier
	v_fma_f32 v4, -v2, v3, 1.0
	v_fmac_f32_e32 v3, v4, v3
	v_div_scale_f32 v4, vcc, 1.0, v50, 1.0
	v_mul_f32_e32 v5, v4, v3
	v_fma_f32 v6, -v2, v5, v4
	v_fmac_f32_e32 v5, v6, v3
	v_fma_f32 v2, -v2, v5, v4
	v_div_fmas_f32 v2, v2, v3, v5
	v_div_fixup_f32 v2, v2, v50, 1.0
	v_add3_u32 v0, s0, v0, v141
	v_pk_mul_f32 v[4:5], v[34:35], v[2:3] op_sel_hi:[1,0]
	v_pk_mul_f32 v[6:7], v[36:37], v[2:3] op_sel_hi:[1,0]
	v_cvt_pk_bf16_f32 v4, v4, v5
	v_cvt_pk_bf16_f32 v5, v6, v7
	v_add_u32_e32 v3, v0, v8
	ds_write_b64 v3, v[4:5] offset:32768
	v_pk_mul_f32 v[4:5], v[38:39], v[2:3] op_sel_hi:[1,0]
	v_pk_mul_f32 v[6:7], v[40:41], v[2:3] op_sel_hi:[1,0]
	v_cvt_pk_bf16_f32 v4, v4, v5
	v_cvt_pk_bf16_f32 v5, v6, v7
	v_xad_u32 v3, v8, 16, v0
	ds_write_b64 v3, v[4:5] offset:32768
	v_pk_mul_f32 v[4:5], v[42:43], v[2:3] op_sel_hi:[1,0]
	v_pk_mul_f32 v[6:7], v[44:45], v[2:3] op_sel_hi:[1,0]
	v_cvt_pk_bf16_f32 v4, v4, v5
	v_cvt_pk_bf16_f32 v5, v6, v7
	v_xad_u32 v3, v8, 32, v0
	ds_write_b64 v3, v[4:5] offset:32768
	v_pk_mul_f32 v[4:5], v[46:47], v[2:3] op_sel_hi:[1,0]
	v_pk_mul_f32 v[6:7], v[48:49], v[2:3] op_sel_hi:[1,0]
	v_cvt_pk_bf16_f32 v4, v4, v5
	v_cvt_pk_bf16_f32 v5, v6, v7
	v_xad_u32 v3, v8, 48, v0
	ds_write_b64 v3, v[4:5] offset:32768
	v_pk_mul_f32 v[4:5], v[18:19], v[2:3] op_sel_hi:[1,0]
	v_pk_mul_f32 v[6:7], v[20:21], v[2:3] op_sel_hi:[1,0]
	v_cvt_pk_bf16_f32 v4, v4, v5
	v_cvt_pk_bf16_f32 v5, v6, v7
	v_xad_u32 v3, v8, 64, v0
	ds_write_b64 v3, v[4:5] offset:32768
	v_pk_mul_f32 v[4:5], v[22:23], v[2:3] op_sel_hi:[1,0]
	v_pk_mul_f32 v[6:7], v[24:25], v[2:3] op_sel_hi:[1,0]
	s_movk_i32 s1, 0x50
	v_cvt_pk_bf16_f32 v4, v4, v5
	v_cvt_pk_bf16_f32 v5, v6, v7
	v_xad_u32 v3, v8, s1, v0
	ds_write_b64 v3, v[4:5] offset:32768
	v_pk_mul_f32 v[4:5], v[26:27], v[2:3] op_sel_hi:[1,0]
	v_pk_mul_f32 v[6:7], v[28:29], v[2:3] op_sel_hi:[1,0]
	s_movk_i32 s1, 0x60
	v_cvt_pk_bf16_f32 v4, v4, v5
	v_cvt_pk_bf16_f32 v5, v6, v7
	v_xad_u32 v3, v8, s1, v0
	ds_write_b64 v3, v[4:5] offset:32768
	v_pk_mul_f32 v[4:5], v[30:31], v[2:3] op_sel_hi:[1,0]
	v_pk_mul_f32 v[2:3], v[32:33], v[2:3] op_sel_hi:[1,0]
	s_movk_i32 s1, 0x70
	v_cvt_pk_bf16_f32 v4, v4, v5
	v_cvt_pk_bf16_f32 v5, v2, v3
	v_xad_u32 v0, v8, s1, v0
	ds_write_b64 v0, v[4:5] offset:32768
	v_lshrrev_b32_e32 v0, 3, v140
	v_lshl_or_b32 v13, s6, 1, v8
	v_xor_b32_e32 v2, v0, v130
	v_lshl_add_u32 v12, v2, 4, s0
	v_or_b32_e32 v14, 0, v0
	v_or_b32_e32 v6, s5, v14
	v_ashrrev_i32_e32 v7, 31, v6
	v_lshlrev_b64 v[36:37], 11, v[6:7]
	v_or_b32_e32 v36, v36, v13
	v_lshl_add_u64 v[6:7], s[64:65], 0, v[36:37]
	global_load_dwordx4 v[20:23], v[6:7], off nt
	v_or_b32_e32 v14, 8, v0
	v_or_b32_e32 v6, s5, v14
	v_ashrrev_i32_e32 v7, 31, v6
	v_lshlrev_b64 v[38:39], 11, v[6:7]
	v_or_b32_e32 v38, v38, v13
	v_lshl_add_u64 v[6:7], s[64:65], 0, v[38:39]
	global_load_dwordx4 v[24:27], v[6:7], off nt
	v_or_b32_e32 v14, 16, v0
	v_or_b32_e32 v6, s5, v14
	v_ashrrev_i32_e32 v7, 31, v6
	v_lshlrev_b64 v[40:41], 11, v[6:7]
	v_or_b32_e32 v40, v40, v13
	v_lshl_add_u64 v[6:7], s[64:65], 0, v[40:41]
	global_load_dwordx4 v[28:31], v[6:7], off nt
	v_or_b32_e32 v14, 24, v0
	v_or_b32_e32 v6, s5, v14
	v_ashrrev_i32_e32 v7, 31, v6
	v_lshlrev_b64 v[42:43], 11, v[6:7]
	v_or_b32_e32 v42, v42, v13
	v_lshl_add_u64 v[6:7], s[64:65], 0, v[42:43]
	global_load_dwordx4 v[32:35], v[6:7], off nt
	v_or_b32_e32 v14, 0, v0
	v_lshl_add_u32 v15, v14, 7, v12
	ds_read_b128 v[44:47], v15 offset:32768
	v_or_b32_e32 v14, 8, v0
	v_lshl_add_u32 v15, v14, 7, v12
	ds_read_b128 v[48:51], v15 offset:32768
	v_or_b32_e32 v14, 16, v0
	v_lshl_add_u32 v15, v14, 7, v12
	ds_read_b128 v[52:55], v15 offset:32768
	v_or_b32_e32 v14, 24, v0
	v_lshl_add_u32 v15, v14, 7, v12
	ds_read_b128 v[56:59], v15 offset:32768
	s_waitcnt vmcnt(3) lgkmcnt(3)
	v_lshlrev_b32_e32 v60, 16, v44
	v_and_b32_e32 v61, 0xffff0000, v44
	v_lshlrev_b32_e32 v62, 16, v20
	v_and_b32_e32 v63, 0xffff0000, v20
	v_lshlrev_b32_e32 v64, 16, v45
	v_and_b32_e32 v65, 0xffff0000, v45
	v_lshlrev_b32_e32 v66, 16, v21
	v_and_b32_e32 v67, 0xffff0000, v21
	v_lshlrev_b32_e32 v68, 16, v46
	v_and_b32_e32 v69, 0xffff0000, v46
	v_lshlrev_b32_e32 v70, 16, v22
	v_and_b32_e32 v71, 0xffff0000, v22
	v_lshlrev_b32_e32 v72, 16, v47
	v_and_b32_e32 v73, 0xffff0000, v47
	v_lshlrev_b32_e32 v74, 16, v23
	v_and_b32_e32 v75, 0xffff0000, v23
	v_pk_mul_f32 v[60:61], v[60:61], v[62:63]
	v_pk_mul_f32 v[64:65], v[64:65], v[66:67]
	v_pk_mul_f32 v[68:69], v[68:69], v[70:71]
	v_pk_mul_f32 v[72:73], v[72:73], v[74:75]
	v_cvt_pk_bf16_f32 v44, v60, v61
	v_cvt_pk_bf16_f32 v45, v64, v65
	v_cvt_pk_bf16_f32 v46, v68, v69
	v_cvt_pk_bf16_f32 v47, v72, v73
	v_lshl_add_u64 v[6:7], s[66:67], 0, v[36:37]
	global_store_dwordx4 v[6:7], v[44:47], off nt
	s_waitcnt vmcnt(3) lgkmcnt(2)
	v_lshlrev_b32_e32 v60, 16, v48
	v_and_b32_e32 v61, 0xffff0000, v48
	v_lshlrev_b32_e32 v62, 16, v24
	v_and_b32_e32 v63, 0xffff0000, v24
	v_lshlrev_b32_e32 v64, 16, v49
	v_and_b32_e32 v65, 0xffff0000, v49
	v_lshlrev_b32_e32 v66, 16, v25
	v_and_b32_e32 v67, 0xffff0000, v25
	v_lshlrev_b32_e32 v68, 16, v50
	v_and_b32_e32 v69, 0xffff0000, v50
	v_lshlrev_b32_e32 v70, 16, v26
	v_and_b32_e32 v71, 0xffff0000, v26
	v_lshlrev_b32_e32 v72, 16, v51
	v_and_b32_e32 v73, 0xffff0000, v51
	v_lshlrev_b32_e32 v74, 16, v27
	v_and_b32_e32 v75, 0xffff0000, v27
	v_pk_mul_f32 v[60:61], v[60:61], v[62:63]
	v_pk_mul_f32 v[64:65], v[64:65], v[66:67]
	v_pk_mul_f32 v[68:69], v[68:69], v[70:71]
	v_pk_mul_f32 v[72:73], v[72:73], v[74:75]
	v_cvt_pk_bf16_f32 v48, v60, v61
	v_cvt_pk_bf16_f32 v49, v64, v65
	v_cvt_pk_bf16_f32 v50, v68, v69
	v_cvt_pk_bf16_f32 v51, v72, v73
	v_lshl_add_u64 v[6:7], s[66:67], 0, v[38:39]
	global_store_dwordx4 v[6:7], v[48:51], off nt
	s_waitcnt vmcnt(3) lgkmcnt(1)
	v_lshlrev_b32_e32 v60, 16, v52
	v_and_b32_e32 v61, 0xffff0000, v52
	v_lshlrev_b32_e32 v62, 16, v28
	v_and_b32_e32 v63, 0xffff0000, v28
	v_lshlrev_b32_e32 v64, 16, v53
	v_and_b32_e32 v65, 0xffff0000, v53
	v_lshlrev_b32_e32 v66, 16, v29
	v_and_b32_e32 v67, 0xffff0000, v29
	v_lshlrev_b32_e32 v68, 16, v54
	v_and_b32_e32 v69, 0xffff0000, v54
	v_lshlrev_b32_e32 v70, 16, v30
	v_and_b32_e32 v71, 0xffff0000, v30
	v_lshlrev_b32_e32 v72, 16, v55
	v_and_b32_e32 v73, 0xffff0000, v55
	v_lshlrev_b32_e32 v74, 16, v31
	v_and_b32_e32 v75, 0xffff0000, v31
	v_pk_mul_f32 v[60:61], v[60:61], v[62:63]
	v_pk_mul_f32 v[64:65], v[64:65], v[66:67]
	v_pk_mul_f32 v[68:69], v[68:69], v[70:71]
	v_pk_mul_f32 v[72:73], v[72:73], v[74:75]
	v_cvt_pk_bf16_f32 v52, v60, v61
	v_cvt_pk_bf16_f32 v53, v64, v65
	v_cvt_pk_bf16_f32 v54, v68, v69
	v_cvt_pk_bf16_f32 v55, v72, v73
	v_lshl_add_u64 v[6:7], s[66:67], 0, v[40:41]
	global_store_dwordx4 v[6:7], v[52:55], off nt
	s_waitcnt vmcnt(3) lgkmcnt(0)
	v_lshlrev_b32_e32 v60, 16, v56
	v_and_b32_e32 v61, 0xffff0000, v56
	v_lshlrev_b32_e32 v62, 16, v32
	v_and_b32_e32 v63, 0xffff0000, v32
	v_lshlrev_b32_e32 v64, 16, v57
	v_and_b32_e32 v65, 0xffff0000, v57
	v_lshlrev_b32_e32 v66, 16, v33
	v_and_b32_e32 v67, 0xffff0000, v33
	v_lshlrev_b32_e32 v68, 16, v58
	v_and_b32_e32 v69, 0xffff0000, v58
	v_lshlrev_b32_e32 v70, 16, v34
	v_and_b32_e32 v71, 0xffff0000, v34
	v_lshlrev_b32_e32 v72, 16, v59
	v_and_b32_e32 v73, 0xffff0000, v59
	v_lshlrev_b32_e32 v74, 16, v35
	v_and_b32_e32 v75, 0xffff0000, v35
	v_pk_mul_f32 v[60:61], v[60:61], v[62:63]
	v_pk_mul_f32 v[64:65], v[64:65], v[66:67]
	v_pk_mul_f32 v[68:69], v[68:69], v[70:71]
	v_pk_mul_f32 v[72:73], v[72:73], v[74:75]
	v_cvt_pk_bf16_f32 v56, v60, v61
	v_cvt_pk_bf16_f32 v57, v64, v65
	v_cvt_pk_bf16_f32 v58, v68, v69
	v_cvt_pk_bf16_f32 v59, v72, v73
	v_lshl_add_u64 v[6:7], s[66:67], 0, v[42:43]
	global_store_dwordx4 v[6:7], v[56:59], off nt
	s_add_i32 s4, s4, s82
	s_cmpk_gt_i32 s4, 0x7f
	s_cbranch_scc1 .LBB0_552

.LBB0_713:
	s_cmp_lt_i32 s88, 18
	s_cselect_b64 s[0:1], -1, 0
	s_cmp_gt_i32 s89, 17
	s_cselect_b64 s[2:3], -1, 0
	s_and_b64 s[0:1], s[0:1], s[2:3]
	s_and_b64 vcc, exec, s[0:1]
	s_cbranch_vccz .LBB0_721
	v_mbcnt_lo_u32_b32 v0, -1, 0
	v_mbcnt_hi_u32_b32 v0, -1, v0
	s_cmpk_gt_i32 s48, 0x7fff
	v_add_u32_e32 v0, s69, v0
	s_cbranch_scc1 .LBB0_721
	v_and_b32_e32 v0, 63, v0
	v_readlane_b32 s0, v252, 0
	v_lshlrev_b32_e32 v0, 4, v0
	v_mov_b32_e32 v1, 0
	v_readlane_b32 s1, v252, 1
	v_readlane_b32 s2, v252, 2
	v_readlane_b32 s3, v252, 3
	v_lshl_add_u64 v[52:53], s[78:79], 0, v[0:1]
	v_lshl_add_u64 v[2:3], s[0:1], 0, v[0:1]
	s_mov_b64 s[0:1], 0x3000
	v_lshl_add_u64 v[0:1], s[2:3], 0, v[0:1]
	v_lshl_add_u64 v[56:57], v[0:1], 0, s[0:1]
	v_and_b32_e32 v0, 64, v211
	v_add_u32_e32 v0, 64, v0
	v_xor_b32_e32 v1, 1, v211
	v_cmp_lt_i32_e32 vcc, v1, v0
	v_lshl_add_u64 v[54:55], v[2:3], 0, s[0:1]
	s_lshl_b32 s16, s82, 5
	v_cndmask_b32_e32 v1, v211, v1, vcc
	v_lshlrev_b32_e32 v60, 2, v1
	v_xor_b32_e32 v1, 2, v211
	v_cmp_lt_i32_e32 vcc, v1, v0
	s_mul_i32 s17, s82, 24
	v_mov_b32_e32 v66, 0x3727c5ac
	v_cndmask_b32_e32 v1, v211, v1, vcc
	v_lshlrev_b32_e32 v61, 2, v1
	v_xor_b32_e32 v1, 4, v211
	v_cmp_lt_i32_e32 vcc, v1, v0
	s_mov_b32 s18, 0xf800000
	v_mov_b32_e32 v67, 0x260
	v_cndmask_b32_e32 v1, v211, v1, vcc
	v_lshlrev_b32_e32 v62, 2, v1
	v_xor_b32_e32 v1, 8, v211
	v_cmp_lt_i32_e32 vcc, v1, v0
	v_readlane_b32 s4, v252, 4
	v_readlane_b32 s5, v252, 5
	v_cndmask_b32_e32 v1, v211, v1, vcc
	v_lshlrev_b32_e32 v63, 2, v1
	v_xor_b32_e32 v1, 16, v211
	v_cmp_lt_i32_e32 vcc, v1, v0
	v_readlane_b32 s6, v252, 6
	v_readlane_b32 s7, v252, 7
	v_cndmask_b32_e32 v1, v211, v1, vcc
	v_lshlrev_b32_e32 v64, 2, v1
	v_xor_b32_e32 v1, 32, v211
	v_cmp_lt_i32_e32 vcc, v1, v0
	s_nop 1
	v_cndmask_b32_e32 v0, v211, v1, vcc
	v_lshlrev_b32_e32 v65, 2, v0
	global_load_dwordx4 v[152:155], v[54:55], off
	global_load_dwordx4 v[168:171], v[56:57], off
	global_load_dwordx4 v[156:159], v[54:55], off offset:1024
	global_load_dwordx4 v[172:175], v[56:57], off offset:1024
	global_load_dwordx4 v[160:163], v[54:55], off offset:2048
	global_load_dwordx4 v[176:179], v[56:57], off offset:2048
	global_load_dwordx4 v[164:167], v[54:55], off offset:3072
	global_load_dwordx4 v[180:183], v[56:57], off offset:3072
	s_waitcnt vmcnt(0)
	s_branch .LBB0_717

.LBB0_717:
	s_add_i32 s10, s96, s48
	s_cmp_lt_i32 s10, 0x8000
	s_cselect_b32 s0, s10, s48
	s_ashr_i32 s1, s0, 31
	s_lshl_b64 s[12:13], s[0:1], 12
	s_add_i32 s6, s97, s48
	s_cmp_lt_i32 s6, 0x8000
	s_cselect_b64 s[8:9], -1, 0
	s_and_b64 s[0:1], s[8:9], exec
	s_cselect_b32 s0, s6, s48
	s_ashr_i32 s1, s0, 31
	s_lshl_b64 s[14:15], s[0:1], 12
	s_add_i32 s2, s17, s48
	s_cmp_lt_i32 s2, 0x8000
	s_cselect_b64 s[4:5], -1, 0
	s_and_b64 s[0:1], s[4:5], exec
	s_cselect_b32 s0, s2, s48
	s_ashr_i32 s49, s48, 31
	s_lshl_b64 s[20:21], s[48:49], 12
	v_lshl_add_u64 v[58:59], v[52:53], 0, s[20:21]
	global_load_dwordx4 v[10:13], v[58:59], off nt
	global_load_dwordx4 v[2:5], v[58:59], off offset:1024 nt
	global_load_dwordx4 v[48:51], v[58:59], off offset:2048 nt
	global_load_dwordx4 v[44:47], v[58:59], off offset:3072 nt
	s_nop 0
	s_nop 0
	s_ashr_i32 s1, s0, 31
	s_lshl_b64 s[0:1], s[0:1], 12
	v_lshl_add_u64 v[84:85], v[52:53], 0, s[0:1]
	v_lshl_add_u64 v[80:81], v[52:53], 0, s[12:13]
	v_lshl_add_u64 v[82:83], v[52:53], 0, s[14:15]
	global_load_dwordx4 v[36:39], v[80:81], off nt
	global_load_dwordx4 v[32:35], v[80:81], off offset:1024 nt
	s_cmpk_gt_i32 s10, 0x7fff
	s_waitcnt vmcnt(2)
	v_mov_b32_e32 v0, v11
	v_mov_b32_e32 v1, v12
	v_mov_b32_e32 v6, v10
	v_mov_b32_e32 v7, v13
	v_mov_b32_e32 v8, v3
	v_mov_b32_e32 v9, v4
	v_mov_b32_e32 v14, v2
	v_mov_b32_e32 v15, v5
	v_pk_add_f32 v[0:1], v[0:1], v[6:7]
	v_pk_add_f32 v[6:7], v[8:9], v[14:15]
	v_add_f32_e32 v14, v0, v1
	v_pk_add_f32 v[0:1], v[6:7], v[6:7] op_sel:[0,1] op_sel_hi:[1,0]
	v_add_f32_e32 v16, v48, v49
	v_add_f32_e32 v18, v50, v51
	v_mov_b32_e32 v21, v44
	v_mov_b32_e32 v17, v46
	v_mov_b32_e32 v19, v47
	v_add_f32_e32 v20, 0, v14
	v_mov_b32_e32 v1, v45
	v_pk_add_f32 v[8:9], v[16:17], v[18:19]
	v_pk_add_f32 v[0:1], v[20:21], v[0:1]
	s_nop 0
	v_pk_add_f32 v[0:1], v[0:1], v[8:9]
	s_nop 0
	v_add_f32_e32 v0, v0, v1
	ds_bpermute_b32 v1, v60, v0
	s_waitcnt lgkmcnt(0)
	v_add_f32_e32 v0, v0, v1
	ds_bpermute_b32 v1, v61, v0
	s_waitcnt lgkmcnt(0)
	v_add_f32_e32 v0, v0, v1
	ds_bpermute_b32 v1, v62, v0
	s_waitcnt lgkmcnt(0)
	v_add_f32_e32 v0, v0, v1
	ds_bpermute_b32 v1, v63, v0
	s_waitcnt lgkmcnt(0)
	v_add_f32_e32 v0, v0, v1
	ds_bpermute_b32 v1, v64, v0
	s_waitcnt lgkmcnt(0)
	v_add_f32_e32 v0, v0, v1
	ds_bpermute_b32 v1, v65, v0
	s_waitcnt lgkmcnt(0)
	v_add_f32_e32 v0, v0, v1
	v_fmamk_f32 v7, v0, 0xba800000, v11
	v_fmamk_f32 v6, v0, 0xba800000, v10
	v_fmamk_f32 v13, v0, 0xba800000, v13
	v_fmac_f32_e32 v12, 0xba800000, v0
	v_fmamk_f32 v41, v0, 0xba800000, v3
	v_fmamk_f32 v40, v0, 0xba800000, v2
	v_fmamk_f32 v5, v0, 0xba800000, v5
	v_fmac_f32_e32 v4, 0xba800000, v0
	v_fmamk_f32 v77, v0, 0xba800000, v49
	v_fmamk_f32 v76, v0, 0xba800000, v48
	v_fmamk_f32 v51, v0, 0xba800000, v51
	v_fmac_f32_e32 v50, 0xba800000, v0
	v_fmamk_f32 v79, v0, 0xba800000, v47
	v_fmamk_f32 v78, v0, 0xba800000, v46
	v_fmamk_f32 v45, v0, 0xba800000, v45
	v_fmac_f32_e32 v44, 0xba800000, v0
	v_pk_mul_f32 v[0:1], v[12:13], v[12:13]
	v_pk_mul_f32 v[2:3], v[6:7], v[6:7]
	v_pk_mul_f32 v[8:9], v[4:5], v[4:5]
	v_pk_mul_f32 v[10:11], v[40:41], v[40:41]
	v_pk_mov_b32 v[18:19], v[2:3], v[0:1] op_sel:[1,0]
	v_mov_b32_e32 v3, v1
	v_pk_mov_b32 v[0:1], v[10:11], v[8:9] op_sel:[1,0]
	v_mov_b32_e32 v11, v9
	v_mul_f32_e32 v17, v44, v44
	v_mul_f32_e32 v14, v77, v77
	v_mul_f32_e32 v16, v51, v51
	v_pk_add_f32 v[2:3], v[18:19], v[2:3]
	v_pk_add_f32 v[0:1], v[0:1], v[10:11]
	v_mul_f32_e32 v20, v45, v45
	v_mul_f32_e32 v21, v78, v78
	v_mul_f32_e32 v22, v79, v79
	v_pk_fma_f32 v[8:9], v[76:77], v[76:77], v[14:15] op_sel_hi:[1,1,0]
	v_pk_fma_f32 v[14:15], v[50:51], v[50:51], v[16:17] op_sel_hi:[1,1,0]
	v_pk_add_f32 v[2:3], v[2:3], v[2:3] op_sel:[0,1] op_sel_hi:[1,0]
	v_pk_add_f32 v[0:1], v[0:1], v[0:1] op_sel:[0,1] op_sel_hi:[1,0]
	v_mov_b32_e32 v9, v21
	v_mov_b32_e32 v15, v22
	v_mov_b32_e32 v3, v17
	v_mov_b32_e32 v1, v20
	v_pk_add_f32 v[8:9], v[8:9], v[14:15]
	v_pk_add_f32 v[0:1], v[2:3], v[0:1]
	global_load_dwordx4 v[20:23], v[82:83], off nt
	global_load_dwordx4 v[16:19], v[82:83], off offset:1024 nt
	v_pk_add_f32 v[0:1], v[0:1], v[8:9]
	s_nop 0
	v_add_f32_e32 v0, v0, v1
	ds_bpermute_b32 v1, v60, v0
	s_waitcnt lgkmcnt(0)
	v_add_f32_e32 v0, v0, v1
	ds_bpermute_b32 v1, v61, v0
	s_waitcnt lgkmcnt(0)
	v_add_f32_e32 v0, v0, v1
	ds_bpermute_b32 v1, v62, v0
	s_waitcnt lgkmcnt(0)
	v_add_f32_e32 v0, v0, v1
	ds_bpermute_b32 v1, v63, v0
	s_waitcnt lgkmcnt(0)
	v_add_f32_e32 v0, v0, v1
	ds_bpermute_b32 v1, v64, v0
	s_waitcnt lgkmcnt(0)
	v_add_f32_e32 v0, v0, v1
	ds_bpermute_b32 v1, v65, v0
	s_waitcnt lgkmcnt(0)
	v_add_f32_e32 v0, v0, v1
	v_fmamk_f32 v0, v0, 0x3a800000, v66
	v_mul_f32_e32 v1, 0x4f800000, v0
	v_cmp_gt_f32_e32 vcc, s18, v0
	s_nop 1
	v_cndmask_b32_e32 v0, v0, v1, vcc
	v_sqrt_f32_e32 v1, v0
	s_nop 0
	v_add_u32_e32 v2, -1, v1
	v_add_u32_e32 v3, 1, v1
	v_fma_f32 v8, -v2, v1, v0
	v_fma_f32 v9, -v3, v1, v0
	v_cmp_ge_f32_e64 s[0:1], 0, v8
	s_nop 1
	v_cndmask_b32_e64 v1, v1, v2, s[0:1]
	v_cmp_lt_f32_e64 s[0:1], 0, v9
	s_nop 1
	v_cndmask_b32_e64 v1, v1, v3, s[0:1]
	v_mul_f32_e32 v2, 0x37800000, v1
	v_cndmask_b32_e32 v1, v1, v2, vcc
	v_cmp_class_f32_e32 vcc, v0, v67
	s_nop 1
	v_cndmask_b32_e32 v14, v1, v0, vcc
	v_div_scale_f32 v15, s[0:1], v14, v14, 1.0
	v_rcp_f32_e32 v42, v15
	v_div_scale_f32 v43, vcc, 1.0, v14, 1.0
	global_load_dwordx4 v[8:11], v[84:85], off nt
	global_load_dwordx4 v[0:3], v[84:85], off offset:1024 nt
	v_fma_f32 v46, -v15, v42, 1.0
	v_fmac_f32_e32 v42, v46, v42
	v_mul_f32_e32 v46, v43, v42
	v_fma_f32 v47, -v15, v46, v43
	v_fmac_f32_e32 v46, v47, v42
	v_fma_f32 v15, -v15, v46, v43
	v_div_fmas_f32 v15, v15, v42, v46
	v_div_fixup_f32 v86, v15, v14, 1.0
	v_pk_mul_f32 v[6:7], v[86:87], v[6:7] op_sel_hi:[0,1]
	v_pk_mul_f32 v[12:13], v[86:87], v[12:13] op_sel_hi:[0,1]
	v_pk_fma_f32 v[14:15], v[154:155], v[12:13], v[170:171]
	v_pk_fma_f32 v[12:13], v[152:153], v[6:7], v[168:169]
	global_store_dwordx4 v[58:59], v[12:15], off nt
	s_nop 0
	s_nop 0
	s_nop 0
	v_pk_mul_f32 v[6:7], v[86:87], v[4:5] op_sel_hi:[0,1]
	v_pk_mul_f32 v[4:5], v[86:87], v[40:41] op_sel_hi:[0,1]
	v_pk_mul_f32 v[50:51], v[86:87], v[50:51] op_sel_hi:[0,1]
	v_pk_mul_f32 v[76:77], v[86:87], v[76:77] op_sel_hi:[0,1]
	v_pk_mul_f32 v[44:45], v[86:87], v[44:45] op_sel_hi:[0,1]
	s_nop 0
	v_pk_fma_f32 v[4:5], v[156:157], v[4:5], v[172:173]
	v_pk_fma_f32 v[6:7], v[158:159], v[6:7], v[174:175]
	global_store_dwordx4 v[58:59], v[4:7], off offset:1024 nt
	s_nop 0
	s_nop 0
	global_load_dwordx4 v[46:49], v[80:81], off offset:2048 nt
	global_load_dwordx4 v[40:43], v[80:81], off offset:3072 nt
	global_load_dwordx4 v[28:31], v[82:83], off offset:2048 nt
	global_load_dwordx4 v[24:27], v[82:83], off offset:3072 nt
	global_load_dwordx4 v[12:15], v[84:85], off offset:2048 nt
	global_load_dwordx4 v[4:7], v[84:85], off offset:3072 nt
	s_nop 0
	v_pk_fma_f32 v[68:69], v[160:161], v[76:77], v[176:177]
	v_pk_fma_f32 v[70:71], v[162:163], v[50:51], v[178:179]
	global_store_dwordx4 v[58:59], v[68:71], off offset:2048 nt
	s_nop 0
	s_nop 0
	s_nop 0
	v_pk_mul_f32 v[50:51], v[86:87], v[78:79] op_sel_hi:[0,1]
	s_waitcnt vmcnt(5)
	v_pk_fma_f32 v[68:69], v[164:165], v[44:45], v[180:181]
	v_pk_fma_f32 v[70:71], v[166:167], v[50:51], v[182:183]
	global_store_dwordx4 v[58:59], v[68:71], off offset:3072 nt
	s_cbranch_scc1 .LBB0_716
	v_mov_b32_e32 v44, v37
	v_mov_b32_e32 v45, v38
	v_mov_b32_e32 v50, v36
	v_mov_b32_e32 v51, v39
	v_pk_add_f32 v[44:45], v[44:45], v[50:51]
	v_mov_b32_e32 v50, v33
	v_mov_b32_e32 v51, v34
	v_mov_b32_e32 v58, v32
	v_mov_b32_e32 v59, v35
	v_pk_add_f32 v[50:51], v[50:51], v[58:59]
	v_add_f32_e32 v44, v44, v45
	v_pk_add_f32 v[50:51], v[50:51], v[50:51] op_sel:[0,1] op_sel_hi:[1,0]
	v_add_f32_e32 v44, 0, v44
	v_add_f32_e32 v58, v46, v47
	v_add_f32_e32 v68, v48, v49
	v_mov_b32_e32 v45, v40
	v_mov_b32_e32 v51, v41
	v_mov_b32_e32 v59, v42
	v_mov_b32_e32 v69, v43
	v_pk_add_f32 v[44:45], v[44:45], v[50:51]
	v_pk_add_f32 v[50:51], v[58:59], v[68:69]
	s_ashr_i32 s11, s10, 31
	v_pk_add_f32 v[44:45], v[44:45], v[50:51]
	s_nop 0
	v_add_f32_e32 v44, v44, v45
	ds_bpermute_b32 v45, v60, v44
	s_waitcnt lgkmcnt(0)
	v_add_f32_e32 v44, v44, v45
	ds_bpermute_b32 v45, v61, v44
	s_waitcnt lgkmcnt(0)
	v_add_f32_e32 v44, v44, v45
	ds_bpermute_b32 v45, v62, v44
	s_waitcnt lgkmcnt(0)
	v_add_f32_e32 v44, v44, v45
	ds_bpermute_b32 v45, v63, v44
	s_waitcnt lgkmcnt(0)
	v_add_f32_e32 v44, v44, v45
	ds_bpermute_b32 v45, v64, v44
	s_waitcnt lgkmcnt(0)
	v_add_f32_e32 v44, v44, v45
	ds_bpermute_b32 v45, v65, v44
	s_waitcnt lgkmcnt(0)
	v_add_f32_e32 v70, v44, v45
	v_fmamk_f32 v37, v70, 0xba800000, v37
	v_fmamk_f32 v36, v70, 0xba800000, v36
	v_fmamk_f32 v39, v70, 0xba800000, v39
	v_fmac_f32_e32 v38, 0xba800000, v70
	v_pk_mul_f32 v[44:45], v[38:39], v[38:39]
	v_pk_mul_f32 v[50:51], v[36:37], v[36:37]
	v_fmamk_f32 v33, v70, 0xba800000, v33
	v_fmamk_f32 v32, v70, 0xba800000, v32
	v_fmamk_f32 v35, v70, 0xba800000, v35
	v_pk_mov_b32 v[58:59], v[50:51], v[44:45] op_sel:[1,0]
	v_mov_b32_e32 v51, v45
	v_fmac_f32_e32 v34, 0xba800000, v70
	v_pk_add_f32 v[44:45], v[58:59], v[50:51]
	v_pk_mul_f32 v[50:51], v[34:35], v[34:35]
	v_pk_mul_f32 v[58:59], v[32:33], v[32:33]
	v_fmamk_f32 v41, v70, 0xba800000, v41
	v_pk_mov_b32 v[68:69], v[58:59], v[50:51] op_sel:[1,0]
	v_mov_b32_e32 v59, v51
	v_pk_add_f32 v[50:51], v[68:69], v[58:59]
	v_fmac_f32_e32 v40, 0xba800000, v70
	v_fmamk_f32 v59, v70, 0xba800000, v43
	v_fmamk_f32 v58, v70, 0xba800000, v42
	v_mul_f32_e32 v68, v40, v40
	v_mul_f32_e32 v69, v41, v41
	v_pk_add_f32 v[42:43], v[44:45], v[44:45] op_sel:[0,1] op_sel_hi:[1,0]
	v_pk_add_f32 v[44:45], v[50:51], v[50:51] op_sel:[0,1] op_sel_hi:[1,0]
	v_fmamk_f32 v47, v70, 0xba800000, v47
	v_mov_b32_e32 v43, v68
	v_mov_b32_e32 v45, v69
	v_fmamk_f32 v46, v70, 0xba800000, v46
	v_fmamk_f32 v49, v70, 0xba800000, v49
	v_pk_add_f32 v[50:51], v[42:43], v[44:45]
	v_mul_f32_e32 v42, v47, v47
	v_fmac_f32_e32 v48, 0xba800000, v70
	v_mul_f32_e32 v70, v58, v58
	v_pk_fma_f32 v[72:73], v[46:47], v[46:47], v[42:43] op_sel_hi:[1,1,0]
	v_mul_f32_e32 v42, v49, v49
	v_mov_b32_e32 v73, v70
	v_pk_fma_f32 v[74:75], v[48:49], v[48:49], v[42:43] op_sel_hi:[1,1,0]
	s_nop 0
	s_nop 0
	v_mul_f32_e32 v76, v59, v59
	v_mov_b32_e32 v75, v76
	v_pk_add_f32 v[72:73], v[72:73], v[74:75]
	s_nop 0
	v_pk_add_f32 v[50:51], v[50:51], v[72:73]
	s_nop 0
	v_add_f32_e32 v50, v50, v51
	ds_bpermute_b32 v51, v60, v50
	s_waitcnt lgkmcnt(0)
	v_add_f32_e32 v50, v50, v51
	ds_bpermute_b32 v51, v61, v50
	s_waitcnt lgkmcnt(0)
	v_add_f32_e32 v50, v50, v51
	ds_bpermute_b32 v51, v62, v50
	s_waitcnt lgkmcnt(0)
	v_add_f32_e32 v50, v50, v51
	ds_bpermute_b32 v51, v63, v50
	s_waitcnt lgkmcnt(0)
	v_add_f32_e32 v50, v50, v51
	ds_bpermute_b32 v51, v64, v50
	s_waitcnt lgkmcnt(0)
	v_add_f32_e32 v50, v50, v51
	ds_bpermute_b32 v51, v65, v50
	s_waitcnt lgkmcnt(0)
	v_add_f32_e32 v50, v50, v51
	v_fmamk_f32 v50, v50, 0x3a800000, v66
	v_mul_f32_e32 v51, 0x4f800000, v50
	v_cmp_gt_f32_e32 vcc, s18, v50
	s_nop 1
	v_cndmask_b32_e32 v50, v50, v51, vcc
	v_sqrt_f32_e32 v51, v50
	s_nop 0
	v_add_u32_e32 v72, -1, v51
	v_fma_f32 v73, -v72, v51, v50
	v_cmp_ge_f32_e64 s[0:1], 0, v73
	v_add_u32_e32 v73, 1, v51
	s_nop 0
	v_cndmask_b32_e64 v72, v51, v72, s[0:1]
	v_fma_f32 v51, -v73, v51, v50
	v_cmp_lt_f32_e64 s[0:1], 0, v51
	s_nop 1
	v_cndmask_b32_e64 v51, v72, v73, s[0:1]
	v_mul_f32_e32 v72, 0x37800000, v51
	v_cndmask_b32_e32 v51, v51, v72, vcc
	v_cmp_class_f32_e32 vcc, v50, v67
	s_nop 1
	v_cndmask_b32_e32 v72, v51, v50, vcc
	v_div_scale_f32 v73, s[0:1], v72, v72, 1.0
	v_rcp_f32_e32 v74, v73
	s_lshl_b64 s[0:1], s[10:11], 12
	v_lshl_add_u64 v[50:51], v[52:53], 0, s[0:1]
	v_fma_f32 v75, -v73, v74, 1.0
	v_fmac_f32_e32 v74, v75, v74
	v_div_scale_f32 v75, vcc, 1.0, v72, 1.0
	v_mul_f32_e32 v76, v75, v74
	v_fma_f32 v77, -v73, v76, v75
	v_fmac_f32_e32 v76, v77, v74
	v_fma_f32 v73, -v73, v76, v75
	v_div_fmas_f32 v73, v73, v74, v76
	v_div_fixup_f32 v72, v73, v72, 1.0
	v_pk_mul_f32 v[36:37], v[72:73], v[36:37] op_sel_hi:[0,1]
	v_pk_mul_f32 v[38:39], v[72:73], v[38:39] op_sel_hi:[0,1]
	s_nop 0
	v_pk_fma_f32 v[38:39], v[154:155], v[38:39], v[170:171]
	v_pk_fma_f32 v[36:37], v[152:153], v[36:37], v[168:169]
	global_store_dwordx4 v[50:51], v[36:39], off nt
	s_nop 0
	s_nop 0
	s_nop 0
	v_pk_mul_f32 v[34:35], v[72:73], v[34:35] op_sel_hi:[0,1]
	v_pk_mul_f32 v[32:33], v[72:73], v[32:33] op_sel_hi:[0,1]
	v_pk_mul_f32 v[40:41], v[72:73], v[40:41] op_sel_hi:[0,1]
	s_andn2_b64 vcc, exec, s[8:9]
	s_nop 0
	v_pk_fma_f32 v[32:33], v[156:157], v[32:33], v[172:173]
	v_pk_fma_f32 v[34:35], v[158:159], v[34:35], v[174:175]
	global_store_dwordx4 v[50:51], v[32:35], off offset:1024 nt
	s_nop 0
	s_nop 0
	s_nop 0
	v_pk_mul_f32 v[42:43], v[72:73], v[48:49] op_sel_hi:[0,1]
	v_pk_mul_f32 v[44:45], v[72:73], v[46:47] op_sel_hi:[0,1]
	s_nop 0
	v_pk_fma_f32 v[32:33], v[160:161], v[44:45], v[176:177]
	v_pk_fma_f32 v[34:35], v[162:163], v[42:43], v[178:179]
	global_store_dwordx4 v[50:51], v[32:35], off offset:2048 nt
	s_nop 0
	s_nop 0
	s_nop 0
	v_pk_mul_f32 v[42:43], v[72:73], v[58:59] op_sel_hi:[0,1]
	s_waitcnt vmcnt(7)
	v_pk_fma_f32 v[32:33], v[164:165], v[40:41], v[180:181]
	v_pk_fma_f32 v[34:35], v[166:167], v[42:43], v[182:183]
	global_store_dwordx4 v[50:51], v[32:35], off offset:3072 nt
	s_cbranch_vccnz .LBB0_716
	s_nop 0
	v_mov_b32_e32 v32, v21
	v_mov_b32_e32 v33, v22
	v_mov_b32_e32 v34, v20
	v_mov_b32_e32 v35, v23
	v_pk_add_f32 v[32:33], v[32:33], v[34:35]
	v_mov_b32_e32 v34, v17
	v_mov_b32_e32 v35, v18
	v_mov_b32_e32 v36, v16
	v_mov_b32_e32 v37, v19
	v_pk_add_f32 v[34:35], v[34:35], v[36:37]
	v_add_f32_e32 v32, v32, v33
	v_pk_add_f32 v[34:35], v[34:35], v[34:35] op_sel:[0,1] op_sel_hi:[1,0]
	v_add_f32_e32 v32, 0, v32
	v_add_f32_e32 v36, v28, v29
	v_add_f32_e32 v38, v30, v31
	v_mov_b32_e32 v33, v24
	v_mov_b32_e32 v35, v25
	v_mov_b32_e32 v37, v26
	v_mov_b32_e32 v39, v27
	v_pk_add_f32 v[32:33], v[32:33], v[34:35]
	v_pk_add_f32 v[34:35], v[36:37], v[38:39]
	s_ashr_i32 s7, s6, 31
	v_pk_add_f32 v[32:33], v[32:33], v[34:35]
	s_nop 0
	v_add_f32_e32 v32, v32, v33
	ds_bpermute_b32 v33, v60, v32
	s_waitcnt lgkmcnt(0)
	v_add_f32_e32 v32, v32, v33
	ds_bpermute_b32 v33, v61, v32
	s_waitcnt lgkmcnt(0)
	v_add_f32_e32 v32, v32, v33
	ds_bpermute_b32 v33, v62, v32
	s_waitcnt lgkmcnt(0)
	v_add_f32_e32 v32, v32, v33
	ds_bpermute_b32 v33, v63, v32
	s_waitcnt lgkmcnt(0)
	v_add_f32_e32 v32, v32, v33
	ds_bpermute_b32 v33, v64, v32
	s_waitcnt lgkmcnt(0)
	v_add_f32_e32 v32, v32, v33
	ds_bpermute_b32 v33, v65, v32
	s_waitcnt lgkmcnt(0)
	v_add_f32_e32 v40, v32, v33
	v_fmamk_f32 v21, v40, 0xba800000, v21
	v_fmamk_f32 v20, v40, 0xba800000, v20
	v_fmamk_f32 v23, v40, 0xba800000, v23
	v_fmac_f32_e32 v22, 0xba800000, v40
	v_pk_mul_f32 v[32:33], v[22:23], v[22:23]
	v_pk_mul_f32 v[34:35], v[20:21], v[20:21]
	v_fmamk_f32 v17, v40, 0xba800000, v17
	v_fmamk_f32 v16, v40, 0xba800000, v16
	v_fmamk_f32 v19, v40, 0xba800000, v19
	v_pk_mov_b32 v[36:37], v[34:35], v[32:33] op_sel:[1,0]
	v_mov_b32_e32 v35, v33
	v_fmac_f32_e32 v18, 0xba800000, v40
	v_pk_add_f32 v[32:33], v[36:37], v[34:35]
	v_pk_mul_f32 v[34:35], v[18:19], v[18:19]
	v_pk_mul_f32 v[36:37], v[16:17], v[16:17]
	v_fmac_f32_e32 v24, 0xba800000, v40
	v_pk_mov_b32 v[38:39], v[36:37], v[34:35] op_sel:[1,0]
	v_mov_b32_e32 v37, v35
	v_pk_add_f32 v[34:35], v[38:39], v[36:37]
	v_fmamk_f32 v36, v40, 0xba800000, v28
	v_fmamk_f32 v39, v40, 0xba800000, v27
	v_fmamk_f32 v38, v40, 0xba800000, v26
	v_fmamk_f32 v25, v40, 0xba800000, v25
	v_mul_f32_e32 v28, v24, v24
	v_pk_add_f32 v[26:27], v[32:33], v[32:33] op_sel:[0,1] op_sel_hi:[1,0]
	v_fmamk_f32 v37, v40, 0xba800000, v29
	v_fmamk_f32 v31, v40, 0xba800000, v31
	v_fmac_f32_e32 v30, 0xba800000, v40
	v_mul_f32_e32 v40, v25, v25
	v_mov_b32_e32 v27, v28
	v_pk_add_f32 v[28:29], v[34:35], v[34:35] op_sel:[0,1] op_sel_hi:[1,0]
	v_mul_f32_e32 v44, v38, v38
	v_mov_b32_e32 v29, v40
	v_pk_add_f32 v[40:41], v[26:27], v[28:29]
	v_mul_f32_e32 v26, v37, v37
	v_pk_fma_f32 v[42:43], v[36:37], v[36:37], v[26:27] op_sel_hi:[1,1,0]
	v_mul_f32_e32 v26, v31, v31
	v_mov_b32_e32 v43, v44
	v_pk_fma_f32 v[44:45], v[30:31], v[30:31], v[26:27] op_sel_hi:[1,1,0]
	s_nop 0
	s_nop 0
	v_mul_f32_e32 v46, v39, v39
	v_mov_b32_e32 v45, v46
	v_pk_add_f32 v[42:43], v[42:43], v[44:45]
	s_nop 0
	v_pk_add_f32 v[40:41], v[40:41], v[42:43]
	s_nop 0
	v_add_f32_e32 v40, v40, v41
	ds_bpermute_b32 v41, v60, v40
	s_waitcnt lgkmcnt(0)
	v_add_f32_e32 v40, v40, v41
	ds_bpermute_b32 v41, v61, v40
	s_waitcnt lgkmcnt(0)
	v_add_f32_e32 v40, v40, v41
	ds_bpermute_b32 v41, v62, v40
	s_waitcnt lgkmcnt(0)
	v_add_f32_e32 v40, v40, v41
	ds_bpermute_b32 v41, v63, v40
	s_waitcnt lgkmcnt(0)
	v_add_f32_e32 v40, v40, v41
	ds_bpermute_b32 v41, v64, v40
	s_waitcnt lgkmcnt(0)
	v_add_f32_e32 v40, v40, v41
	ds_bpermute_b32 v41, v65, v40
	s_waitcnt lgkmcnt(0)
	v_add_f32_e32 v40, v40, v41
	v_fmamk_f32 v40, v40, 0x3a800000, v66
	v_mul_f32_e32 v41, 0x4f800000, v40
	v_cmp_gt_f32_e32 vcc, s18, v40
	s_nop 1
	v_cndmask_b32_e32 v40, v40, v41, vcc
	v_sqrt_f32_e32 v41, v40
	s_nop 0
	v_add_u32_e32 v42, -1, v41
	v_fma_f32 v43, -v42, v41, v40
	v_cmp_ge_f32_e64 s[0:1], 0, v43
	v_add_u32_e32 v43, 1, v41
	s_nop 0
	v_cndmask_b32_e64 v42, v41, v42, s[0:1]
	v_fma_f32 v41, -v43, v41, v40
	v_cmp_lt_f32_e64 s[0:1], 0, v41
	s_nop 1
	v_cndmask_b32_e64 v41, v42, v43, s[0:1]
	v_mul_f32_e32 v42, 0x37800000, v41
	v_cndmask_b32_e32 v41, v41, v42, vcc
	v_cmp_class_f32_e32 vcc, v40, v67
	s_nop 1
	v_cndmask_b32_e32 v42, v41, v40, vcc
	v_div_scale_f32 v43, s[0:1], v42, v42, 1.0
	v_rcp_f32_e32 v44, v43
	s_lshl_b64 s[0:1], s[6:7], 12
	v_lshl_add_u64 v[40:41], v[52:53], 0, s[0:1]
	v_fma_f32 v45, -v43, v44, 1.0
	v_fmac_f32_e32 v44, v45, v44
	v_div_scale_f32 v45, vcc, 1.0, v42, 1.0
	v_mul_f32_e32 v46, v45, v44
	v_fma_f32 v47, -v43, v46, v45
	v_fmac_f32_e32 v46, v47, v44
	v_fma_f32 v43, -v43, v46, v45
	v_div_fmas_f32 v43, v43, v44, v46
	v_div_fixup_f32 v42, v43, v42, 1.0
	v_pk_mul_f32 v[20:21], v[42:43], v[20:21] op_sel_hi:[0,1]
	v_pk_mul_f32 v[22:23], v[42:43], v[22:23] op_sel_hi:[0,1]
	s_nop 0
	v_pk_fma_f32 v[22:23], v[154:155], v[22:23], v[170:171]
	v_pk_fma_f32 v[20:21], v[152:153], v[20:21], v[168:169]
	global_store_dwordx4 v[40:41], v[20:23], off nt
	s_nop 0
	s_nop 0
	s_nop 0
	v_pk_mul_f32 v[18:19], v[42:43], v[18:19] op_sel_hi:[0,1]
	v_pk_mul_f32 v[16:17], v[42:43], v[16:17] op_sel_hi:[0,1]
	v_pk_mul_f32 v[24:25], v[42:43], v[24:25] op_sel_hi:[0,1]
	s_andn2_b64 vcc, exec, s[4:5]
	s_nop 0
	v_pk_fma_f32 v[16:17], v[156:157], v[16:17], v[172:173]
	v_pk_fma_f32 v[18:19], v[158:159], v[18:19], v[174:175]
	global_store_dwordx4 v[40:41], v[16:19], off offset:1024 nt
	s_nop 0
	s_nop 0
	s_nop 0
	v_pk_mul_f32 v[26:27], v[42:43], v[30:31] op_sel_hi:[0,1]
	v_pk_mul_f32 v[28:29], v[42:43], v[36:37] op_sel_hi:[0,1]
	s_nop 0
	v_pk_fma_f32 v[16:17], v[160:161], v[28:29], v[176:177]
	v_pk_fma_f32 v[18:19], v[162:163], v[26:27], v[178:179]
	global_store_dwordx4 v[40:41], v[16:19], off offset:2048 nt
	s_nop 0
	s_nop 0
	s_nop 0
	v_pk_mul_f32 v[26:27], v[42:43], v[38:39] op_sel_hi:[0,1]
	s_waitcnt vmcnt(9)
	v_pk_fma_f32 v[16:17], v[164:165], v[24:25], v[180:181]
	v_pk_fma_f32 v[18:19], v[166:167], v[26:27], v[182:183]
	global_store_dwordx4 v[40:41], v[16:19], off offset:3072 nt
	s_cbranch_vccnz .LBB0_716
	s_nop 0
	v_mov_b32_e32 v16, v9
	v_mov_b32_e32 v17, v10
	v_mov_b32_e32 v18, v8
	v_mov_b32_e32 v19, v11
	v_pk_add_f32 v[16:17], v[16:17], v[18:19]
	v_mov_b32_e32 v18, v1
	v_mov_b32_e32 v19, v2
	v_mov_b32_e32 v20, v0
	v_mov_b32_e32 v21, v3
	v_pk_add_f32 v[18:19], v[18:19], v[20:21]
	v_add_f32_e32 v16, v16, v17
	v_pk_add_f32 v[18:19], v[18:19], v[18:19] op_sel:[0,1] op_sel_hi:[1,0]
	v_add_f32_e32 v16, 0, v16
	v_add_f32_e32 v20, v12, v13
	v_add_f32_e32 v22, v14, v15
	v_mov_b32_e32 v17, v4
	v_mov_b32_e32 v19, v5
	v_mov_b32_e32 v21, v6
	v_mov_b32_e32 v23, v7
	v_pk_add_f32 v[16:17], v[16:17], v[18:19]
	v_pk_add_f32 v[18:19], v[20:21], v[22:23]
	s_ashr_i32 s3, s2, 31
	v_pk_add_f32 v[16:17], v[16:17], v[18:19]
	s_nop 0
	v_add_f32_e32 v16, v16, v17
	ds_bpermute_b32 v17, v60, v16
	s_waitcnt lgkmcnt(0)
	v_add_f32_e32 v16, v16, v17
	ds_bpermute_b32 v17, v61, v16
	s_waitcnt lgkmcnt(0)
	v_add_f32_e32 v16, v16, v17
	ds_bpermute_b32 v17, v62, v16
	s_waitcnt lgkmcnt(0)
	v_add_f32_e32 v16, v16, v17
	ds_bpermute_b32 v17, v63, v16
	s_waitcnt lgkmcnt(0)
	v_add_f32_e32 v16, v16, v17
	ds_bpermute_b32 v17, v64, v16
	s_waitcnt lgkmcnt(0)
	v_add_f32_e32 v16, v16, v17
	ds_bpermute_b32 v17, v65, v16
	s_waitcnt lgkmcnt(0)
	v_add_f32_e32 v26, v16, v17
	v_fmamk_f32 v21, v26, 0xba800000, v9
	v_fmamk_f32 v20, v26, 0xba800000, v8
	v_fmamk_f32 v11, v26, 0xba800000, v11
	v_fmac_f32_e32 v10, 0xba800000, v26
	v_pk_mul_f32 v[8:9], v[10:11], v[10:11]
	v_pk_mul_f32 v[16:17], v[20:21], v[20:21]
	v_fmamk_f32 v1, v26, 0xba800000, v1
	v_fmamk_f32 v0, v26, 0xba800000, v0
	v_fmamk_f32 v3, v26, 0xba800000, v3
	v_pk_mov_b32 v[18:19], v[16:17], v[8:9] op_sel:[1,0]
	v_mov_b32_e32 v17, v9
	v_fmac_f32_e32 v2, 0xba800000, v26
	v_pk_add_f32 v[8:9], v[18:19], v[16:17]
	v_pk_mul_f32 v[16:17], v[2:3], v[2:3]
	v_pk_mul_f32 v[18:19], v[0:1], v[0:1]
	v_fmamk_f32 v5, v26, 0xba800000, v5
	v_pk_mov_b32 v[22:23], v[18:19], v[16:17] op_sel:[1,0]
	v_mov_b32_e32 v19, v17
	v_pk_add_f32 v[16:17], v[22:23], v[18:19]
	v_fmac_f32_e32 v4, 0xba800000, v26
	v_fmamk_f32 v23, v26, 0xba800000, v13
	v_fmamk_f32 v22, v26, 0xba800000, v12
	v_fmamk_f32 v25, v26, 0xba800000, v7
	v_fmamk_f32 v24, v26, 0xba800000, v6
	v_mul_f32_e32 v12, v4, v4
	v_mul_f32_e32 v13, v5, v5
	v_pk_add_f32 v[6:7], v[8:9], v[8:9] op_sel:[0,1] op_sel_hi:[1,0]
	v_pk_add_f32 v[8:9], v[16:17], v[16:17] op_sel:[0,1] op_sel_hi:[1,0]
	v_mov_b32_e32 v7, v12
	v_mov_b32_e32 v9, v13
	v_fmamk_f32 v15, v26, 0xba800000, v15
	v_pk_add_f32 v[12:13], v[6:7], v[8:9]
	v_mul_f32_e32 v6, v23, v23
	v_fmac_f32_e32 v14, 0xba800000, v26
	v_mul_f32_e32 v18, v24, v24
	v_pk_fma_f32 v[26:27], v[22:23], v[22:23], v[6:7] op_sel_hi:[1,1,0]
	v_mul_f32_e32 v6, v15, v15
	v_mov_b32_e32 v27, v18
	v_pk_fma_f32 v[28:29], v[14:15], v[14:15], v[6:7] op_sel_hi:[1,1,0]
	s_nop 0
	s_nop 0
	v_mul_f32_e32 v30, v25, v25
	v_mov_b32_e32 v29, v30
	v_pk_add_f32 v[26:27], v[26:27], v[28:29]
	s_nop 0
	v_pk_add_f32 v[12:13], v[12:13], v[26:27]
	s_nop 0
	v_add_f32_e32 v12, v12, v13
	ds_bpermute_b32 v13, v60, v12
	s_waitcnt lgkmcnt(0)
	v_add_f32_e32 v12, v12, v13
	ds_bpermute_b32 v13, v61, v12
	s_waitcnt lgkmcnt(0)
	v_add_f32_e32 v12, v12, v13
	ds_bpermute_b32 v13, v62, v12
	s_waitcnt lgkmcnt(0)
	v_add_f32_e32 v12, v12, v13
	ds_bpermute_b32 v13, v63, v12
	s_waitcnt lgkmcnt(0)
	v_add_f32_e32 v12, v12, v13
	ds_bpermute_b32 v13, v64, v12
	s_waitcnt lgkmcnt(0)
	v_add_f32_e32 v12, v12, v13
	ds_bpermute_b32 v13, v65, v12
	s_waitcnt lgkmcnt(0)
	v_add_f32_e32 v12, v12, v13
	v_fmamk_f32 v12, v12, 0x3a800000, v66
	v_mul_f32_e32 v13, 0x4f800000, v12
	v_cmp_gt_f32_e32 vcc, s18, v12
	s_nop 1
	v_cndmask_b32_e32 v12, v12, v13, vcc
	v_sqrt_f32_e32 v13, v12
	s_nop 0
	v_add_u32_e32 v26, -1, v13
	v_fma_f32 v27, -v26, v13, v12
	v_cmp_ge_f32_e64 s[0:1], 0, v27
	v_add_u32_e32 v27, 1, v13
	s_nop 0
	v_cndmask_b32_e64 v26, v13, v26, s[0:1]
	v_fma_f32 v13, -v27, v13, v12
	v_cmp_lt_f32_e64 s[0:1], 0, v13
	s_nop 1
	v_cndmask_b32_e64 v13, v26, v27, s[0:1]
	v_mul_f32_e32 v26, 0x37800000, v13
	v_cndmask_b32_e32 v13, v13, v26, vcc
	v_cmp_class_f32_e32 vcc, v12, v67
	s_nop 1
	v_cndmask_b32_e32 v12, v13, v12, vcc
	v_div_scale_f32 v13, s[0:1], v12, v12, 1.0
	v_rcp_f32_e32 v28, v13
	s_lshl_b64 s[0:1], s[2:3], 12
	v_lshl_add_u64 v[26:27], v[52:53], 0, s[0:1]
	v_fma_f32 v29, -v13, v28, 1.0
	v_fmac_f32_e32 v28, v29, v28
	v_div_scale_f32 v29, vcc, 1.0, v12, 1.0
	v_mul_f32_e32 v30, v29, v28
	v_fma_f32 v31, -v13, v30, v29
	v_fmac_f32_e32 v30, v31, v28
	v_fma_f32 v13, -v13, v30, v29
	v_div_fmas_f32 v13, v13, v28, v30
	v_div_fixup_f32 v28, v13, v12, 1.0
	v_pk_mul_f32 v[12:13], v[28:29], v[20:21] op_sel_hi:[0,1]
	v_pk_mul_f32 v[10:11], v[28:29], v[10:11] op_sel_hi:[0,1]
	s_nop 0
	v_pk_fma_f32 v[8:9], v[154:155], v[10:11], v[170:171]
	v_pk_fma_f32 v[6:7], v[152:153], v[12:13], v[168:169]
	global_store_dwordx4 v[26:27], v[6:9], off nt
	s_nop 0
	s_nop 0
	s_nop 0
	v_pk_mul_f32 v[2:3], v[28:29], v[2:3] op_sel_hi:[0,1]
	v_pk_mul_f32 v[0:1], v[28:29], v[0:1] op_sel_hi:[0,1]
	v_pk_mul_f32 v[4:5], v[28:29], v[4:5] op_sel_hi:[0,1]
	s_nop 0
	v_pk_fma_f32 v[0:1], v[156:157], v[0:1], v[172:173]
	v_pk_fma_f32 v[2:3], v[158:159], v[2:3], v[174:175]
	global_store_dwordx4 v[26:27], v[0:3], off offset:1024 nt
	s_nop 0
	s_nop 0
	s_nop 0
	v_pk_mul_f32 v[10:11], v[28:29], v[14:15] op_sel_hi:[0,1]
	v_pk_mul_f32 v[12:13], v[28:29], v[22:23] op_sel_hi:[0,1]
	s_nop 0
	v_pk_fma_f32 v[0:1], v[160:161], v[12:13], v[176:177]
	v_pk_fma_f32 v[2:3], v[162:163], v[10:11], v[178:179]
	global_store_dwordx4 v[26:27], v[0:3], off offset:2048 nt
	s_nop 0
	s_nop 0
	s_nop 0
	v_pk_mul_f32 v[10:11], v[28:29], v[24:25] op_sel_hi:[0,1]
	s_nop 0
	v_pk_fma_f32 v[0:1], v[164:165], v[4:5], v[180:181]
	v_pk_fma_f32 v[2:3], v[166:167], v[10:11], v[182:183]
	global_store_dwordx4 v[26:27], v[0:3], off offset:3072 nt
	s_branch .LBB0_716
